# prologue weight transposes: all 64 row loads of a 64x64 item in flight (scalar base + lane offset) instead of 16 at a time; 17/19 item split between the two workgroup halves
# speedup vs baseline: 1.0026x; 1.0026x over previous
.LBB0_23:
	s_or_b64 exec, exec, s[10:11]
	s_lshl_b32 s63, s62, 3
	v_add_u32_e32 v1, s63, v34
	s_mov_b32 s0, 0x9000
	s_lshl_b32 s82, s94, 3
	s_cmp_eq_u32 s94, 0x100
	s_cbranch_scc0 .Ltr_start
	s_movk_i32 s82, 0x400
	s_cmp_lt_u32 s62, 0x80
	s_cbranch_scc1 .Ltr_start
	v_add_u32_e32 v1, 0x4000, v1
.Ltr_start:
	v_cmp_gt_i32_e32 vcc, s0, v1
	s_barrier
	s_and_saveexec_b64 s[0:1], vcc
	s_cbranch_execz .LBB0_70
	v_lshrrev_b32_e32 v39, 3, v4
	v_lshlrev_b32_e32 v4, 3, v4
	v_and_b32_e32 v4, 56, v4
	s_movk_i32 s4, 0x4100
	v_mul_u32_u24_e32 v10, 0x104, v4
	v_lshlrev_b32_e32 v4, 1, v4
	v_mov_b32_e32 v5, 0
	v_mul_lo_u32 v3, v34, s4
	v_lshl_add_u64 v[6:7], s[8:9], 0, v[4:5]
	s_mov_b64 s[4:5], 0x11000000
	v_add_u32_e32 v3, 0, v3
	v_lshl_add_u64 v[8:9], v[6:7], 0, s[4:5]
	v_lshlrev_b32_e32 v4, 2, v39
	s_mov_b64 s[4:5], 0xa000000
	v_add3_u32 v40, v3, v10, v4
	v_lshl_add_u64 v[10:11], v[6:7], 0, s[4:5]
	s_mov_b64 s[4:5], 0xf000000
	v_lshl_add_u64 v[12:13], v[6:7], 0, s[4:5]
	s_mov_b64 s[4:5], 0x3000000
	v_lshl_add_u64 v[14:15], v[6:7], 0, s[4:5]
	s_mov_b64 s[4:5], 0x10000000
	v_lshl_add_u64 v[16:17], v[6:7], 0, s[4:5]
	s_mov_b64 s[4:5], 0x6000000
	v_lshl_add_u64 v[18:19], v[6:7], 0, s[4:5]
	s_mov_b64 s[4:5], 0xe000000
	v_add_u32_e32 v48, 0xffff7800, v1
	v_add_u32_e32 v49, 0xffff9800, v1
	v_add_u32_e32 v50, 0xffffa000, v1
	v_add_u32_e32 v52, 0xffffc000, v1
	v_add_u32_e32 v53, 0xffffe000, v1
	v_add_u32_e32 v54, 0xffffe800, v1
	v_add_u32_e32 v38, v3, v2
	v_or_b32_e32 v41, 8, v39
	v_or_b32_e32 v42, 16, v39
	v_or_b32_e32 v43, 24, v39
	v_or_b32_e32 v44, 32, v39
	v_or_b32_e32 v45, 40, v39
	v_or_b32_e32 v46, 48, v39
	v_or_b32_e32 v47, 56, v39
	v_lshl_add_u64 v[20:21], v[6:7], 0, s[4:5]
	v_mov_b32_e32 v3, v5
	v_lshlrev_b32_e32 v22, 6, v48
	s_lshl_b32 s22, s82, 6
	v_lshlrev_b32_e32 v24, 6, v49
	v_lshlrev_b32_e32 v26, 6, v50
	v_add_u32_e32 v51, 0xffffb800, v1
	v_lshlrev_b32_e32 v28, 6, v52
	v_lshlrev_b32_e32 v30, 6, v53
	v_lshlrev_b32_e32 v32, 6, v54
	v_lshlrev_b32_e32 v55, 6, v1
	s_mov_b64 s[4:5], 0
	s_movk_i32 s23, 0x17ff
	s_movk_i32 s28, 0x1fff
	s_movk_i32 s29, 0x3fff
	s_movk_i32 s30, 0x47ff
	s_movk_i32 s31, 0x5fff
	s_movk_i32 s33, 0x67ff
	s_mov_b32 s34, 0x87ff
	s_mov_b32 s35, 0x80000
	s_movk_i32 s36, 0xff40
	s_mov_b32 s37, 0xc000
	s_mov_b32 s38, 0x60000
	s_mov_b32 s39, 0x90000
	s_mov_b32 s40, 0x2aaaaaab
	s_movk_i32 s41, 0x3000
	s_mov_b32 s42, 0x8fff
	s_cmp_eq_u32 s94, 0x100
	s_cbranch_scc0 .Ltr_lim
	s_cmp_lt_u32 s62, 0x80
	s_cbranch_scc0 .Ltr_lim
	s_movk_i32 s42, 0x43ff
.Ltr_lim:
	s_branch .LBB0_26

.LBB0_34:
	v_readfirstlane_b32 s20, v34
	v_readfirstlane_b32 s21, v35
	s_nop 4
	v_subrev_u32_e32 v124, s20, v34
	s_add_u32 s20, s20, 0x2000000
	s_addc_u32 s21, s21, 0
	global_load_dword v60, v124, s[20:21] nt
	s_add_u32 s20, s20, 0x2000
	s_addc_u32 s21, s21, 0
	global_load_dword v61, v124, s[20:21] nt
	s_add_u32 s20, s20, 0x2000
	s_addc_u32 s21, s21, 0
	global_load_dword v62, v124, s[20:21] nt
	s_add_u32 s20, s20, 0x2000
	s_addc_u32 s21, s21, 0
	global_load_dword v63, v124, s[20:21] nt
	s_add_u32 s20, s20, 0x2000
	s_addc_u32 s21, s21, 0
	global_load_dword v64, v124, s[20:21] nt
	s_add_u32 s20, s20, 0x2000
	s_addc_u32 s21, s21, 0
	global_load_dword v65, v124, s[20:21] nt
	s_add_u32 s20, s20, 0x2000
	s_addc_u32 s21, s21, 0
	global_load_dword v66, v124, s[20:21] nt
	s_add_u32 s20, s20, 0x2000
	s_addc_u32 s21, s21, 0
	global_load_dword v67, v124, s[20:21] nt
	s_add_u32 s20, s20, 0x2000
	s_addc_u32 s21, s21, 0
	global_load_dword v68, v124, s[20:21] nt
	s_add_u32 s20, s20, 0x2000
	s_addc_u32 s21, s21, 0
	global_load_dword v69, v124, s[20:21] nt
	s_add_u32 s20, s20, 0x2000
	s_addc_u32 s21, s21, 0
	global_load_dword v70, v124, s[20:21] nt
	s_add_u32 s20, s20, 0x2000
	s_addc_u32 s21, s21, 0
	global_load_dword v71, v124, s[20:21] nt
	s_add_u32 s20, s20, 0x2000
	s_addc_u32 s21, s21, 0
	global_load_dword v72, v124, s[20:21] nt
	s_add_u32 s20, s20, 0x2000
	s_addc_u32 s21, s21, 0
	global_load_dword v73, v124, s[20:21] nt
	s_add_u32 s20, s20, 0x2000
	s_addc_u32 s21, s21, 0
	global_load_dword v74, v124, s[20:21] nt
	s_add_u32 s20, s20, 0x2000
	s_addc_u32 s21, s21, 0
	global_load_dword v75, v124, s[20:21] nt
	s_add_u32 s20, s20, 0x2000
	s_addc_u32 s21, s21, 0
	global_load_dword v76, v124, s[20:21] nt
	s_add_u32 s20, s20, 0x2000
	s_addc_u32 s21, s21, 0
	global_load_dword v77, v124, s[20:21] nt
	s_add_u32 s20, s20, 0x2000
	s_addc_u32 s21, s21, 0
	global_load_dword v78, v124, s[20:21] nt
	s_add_u32 s20, s20, 0x2000
	s_addc_u32 s21, s21, 0
	global_load_dword v79, v124, s[20:21] nt
	s_add_u32 s20, s20, 0x2000
	s_addc_u32 s21, s21, 0
	global_load_dword v80, v124, s[20:21] nt
	s_add_u32 s20, s20, 0x2000
	s_addc_u32 s21, s21, 0
	global_load_dword v81, v124, s[20:21] nt
	s_add_u32 s20, s20, 0x2000
	s_addc_u32 s21, s21, 0
	global_load_dword v82, v124, s[20:21] nt
	s_add_u32 s20, s20, 0x2000
	s_addc_u32 s21, s21, 0
	global_load_dword v83, v124, s[20:21] nt
	s_add_u32 s20, s20, 0x2000
	s_addc_u32 s21, s21, 0
	global_load_dword v84, v124, s[20:21] nt
	s_add_u32 s20, s20, 0x2000
	s_addc_u32 s21, s21, 0
	global_load_dword v85, v124, s[20:21] nt
	s_add_u32 s20, s20, 0x2000
	s_addc_u32 s21, s21, 0
	global_load_dword v86, v124, s[20:21] nt
	s_add_u32 s20, s20, 0x2000
	s_addc_u32 s21, s21, 0
	global_load_dword v87, v124, s[20:21] nt
	s_add_u32 s20, s20, 0x2000
	s_addc_u32 s21, s21, 0
	global_load_dword v88, v124, s[20:21] nt
	s_add_u32 s20, s20, 0x2000
	s_addc_u32 s21, s21, 0
	global_load_dword v89, v124, s[20:21] nt
	s_add_u32 s20, s20, 0x2000
	s_addc_u32 s21, s21, 0
	global_load_dword v90, v124, s[20:21] nt
	s_add_u32 s20, s20, 0x2000
	s_addc_u32 s21, s21, 0
	global_load_dword v91, v124, s[20:21] nt
	s_add_u32 s20, s20, 0x2000
	s_addc_u32 s21, s21, 0
	global_load_dword v92, v124, s[20:21] nt
	s_add_u32 s20, s20, 0x2000
	s_addc_u32 s21, s21, 0
	global_load_dword v93, v124, s[20:21] nt
	s_add_u32 s20, s20, 0x2000
	s_addc_u32 s21, s21, 0
	global_load_dword v94, v124, s[20:21] nt
	s_add_u32 s20, s20, 0x2000
	s_addc_u32 s21, s21, 0
	global_load_dword v95, v124, s[20:21] nt
	s_add_u32 s20, s20, 0x2000
	s_addc_u32 s21, s21, 0
	global_load_dword v96, v124, s[20:21] nt
	s_add_u32 s20, s20, 0x2000
	s_addc_u32 s21, s21, 0
	global_load_dword v97, v124, s[20:21] nt
	s_add_u32 s20, s20, 0x2000
	s_addc_u32 s21, s21, 0
	global_load_dword v98, v124, s[20:21] nt
	s_add_u32 s20, s20, 0x2000
	s_addc_u32 s21, s21, 0
	global_load_dword v99, v124, s[20:21] nt
	s_add_u32 s20, s20, 0x2000
	s_addc_u32 s21, s21, 0
	global_load_dword v100, v124, s[20:21] nt
	s_add_u32 s20, s20, 0x2000
	s_addc_u32 s21, s21, 0
	global_load_dword v101, v124, s[20:21] nt
	s_add_u32 s20, s20, 0x2000
	s_addc_u32 s21, s21, 0
	global_load_dword v102, v124, s[20:21] nt
	s_add_u32 s20, s20, 0x2000
	s_addc_u32 s21, s21, 0
	global_load_dword v103, v124, s[20:21] nt
	s_add_u32 s20, s20, 0x2000
	s_addc_u32 s21, s21, 0
	global_load_dword v104, v124, s[20:21] nt
	s_add_u32 s20, s20, 0x2000
	s_addc_u32 s21, s21, 0
	global_load_dword v105, v124, s[20:21] nt
	s_add_u32 s20, s20, 0x2000
	s_addc_u32 s21, s21, 0
	global_load_dword v106, v124, s[20:21] nt
	s_add_u32 s20, s20, 0x2000
	s_addc_u32 s21, s21, 0
	global_load_dword v107, v124, s[20:21] nt
	s_add_u32 s20, s20, 0x2000
	s_addc_u32 s21, s21, 0
	global_load_dword v108, v124, s[20:21] nt
	s_add_u32 s20, s20, 0x2000
	s_addc_u32 s21, s21, 0
	global_load_dword v109, v124, s[20:21] nt
	s_add_u32 s20, s20, 0x2000
	s_addc_u32 s21, s21, 0
	global_load_dword v110, v124, s[20:21] nt
	s_add_u32 s20, s20, 0x2000
	s_addc_u32 s21, s21, 0
	global_load_dword v111, v124, s[20:21] nt
	s_add_u32 s20, s20, 0x2000
	s_addc_u32 s21, s21, 0
	global_load_dword v112, v124, s[20:21] nt
	s_add_u32 s20, s20, 0x2000
	s_addc_u32 s21, s21, 0
	global_load_dword v113, v124, s[20:21] nt
	s_add_u32 s20, s20, 0x2000
	s_addc_u32 s21, s21, 0
	global_load_dword v114, v124, s[20:21] nt
	s_add_u32 s20, s20, 0x2000
	s_addc_u32 s21, s21, 0
	global_load_dword v115, v124, s[20:21] nt
	s_add_u32 s20, s20, 0x2000
	s_addc_u32 s21, s21, 0
	global_load_dword v116, v124, s[20:21] nt
	s_add_u32 s20, s20, 0x2000
	s_addc_u32 s21, s21, 0
	global_load_dword v117, v124, s[20:21] nt
	s_add_u32 s20, s20, 0x2000
	s_addc_u32 s21, s21, 0
	global_load_dword v118, v124, s[20:21] nt
	s_add_u32 s20, s20, 0x2000
	s_addc_u32 s21, s21, 0
	global_load_dword v119, v124, s[20:21] nt
	s_add_u32 s20, s20, 0x2000
	s_addc_u32 s21, s21, 0
	global_load_dword v120, v124, s[20:21] nt
	s_add_u32 s20, s20, 0x2000
	s_addc_u32 s21, s21, 0
	global_load_dword v121, v124, s[20:21] nt
	s_add_u32 s20, s20, 0x2000
	s_addc_u32 s21, s21, 0
	global_load_dword v122, v124, s[20:21] nt
	s_add_u32 s20, s20, 0x2000
	s_addc_u32 s21, s21, 0
	global_load_dword v123, v124, s[20:21] nt
	s_waitcnt vmcnt(62)
	ds_write2_b32 v4, v60, v61 offset1:65
	s_waitcnt vmcnt(60)
	ds_write2_b32 v4, v62, v63 offset0:130 offset1:195
	v_add_u32_e32 v125, 0x400, v4
	s_waitcnt vmcnt(58)
	ds_write2_b32 v125, v64, v65 offset0:4 offset1:69
	s_waitcnt vmcnt(56)
	ds_write2_b32 v125, v66, v67 offset0:134 offset1:199
	v_add_u32_e32 v125, 0x800, v4
	s_waitcnt vmcnt(54)
	ds_write2_b32 v125, v68, v69 offset0:8 offset1:73
	s_waitcnt vmcnt(52)
	ds_write2_b32 v125, v70, v71 offset0:138 offset1:203
	v_add_u32_e32 v125, 0xc00, v4
	s_waitcnt vmcnt(50)
	ds_write2_b32 v125, v72, v73 offset0:12 offset1:77
	s_waitcnt vmcnt(48)
	ds_write2_b32 v125, v74, v75 offset0:142 offset1:207
	v_add_u32_e32 v125, 0x1040, v4
	s_waitcnt vmcnt(46)
	ds_write2_b32 v125, v76, v77 offset1:65
	s_waitcnt vmcnt(44)
	ds_write2_b32 v125, v78, v79 offset0:130 offset1:195
	v_add_u32_e32 v125, 0x1440, v4
	s_waitcnt vmcnt(42)
	ds_write2_b32 v125, v80, v81 offset0:4 offset1:69
	s_waitcnt vmcnt(40)
	ds_write2_b32 v125, v82, v83 offset0:134 offset1:199
	v_add_u32_e32 v125, 0x1840, v4
	s_waitcnt vmcnt(38)
	ds_write2_b32 v125, v84, v85 offset0:8 offset1:73
	s_waitcnt vmcnt(36)
	ds_write2_b32 v125, v86, v87 offset0:138 offset1:203
	v_add_u32_e32 v125, 0x1c40, v4
	s_waitcnt vmcnt(34)
	ds_write2_b32 v125, v88, v89 offset0:12 offset1:77
	s_waitcnt vmcnt(32)
	ds_write2_b32 v125, v90, v91 offset0:142 offset1:207
	v_add_u32_e32 v125, 0x2080, v4
	s_waitcnt vmcnt(30)
	ds_write2_b32 v125, v92, v93 offset1:65
	s_waitcnt vmcnt(28)
	ds_write2_b32 v125, v94, v95 offset0:130 offset1:195
	v_add_u32_e32 v125, 0x2480, v4
	s_waitcnt vmcnt(26)
	ds_write2_b32 v125, v96, v97 offset0:4 offset1:69
	s_waitcnt vmcnt(24)
	ds_write2_b32 v125, v98, v99 offset0:134 offset1:199
	v_add_u32_e32 v125, 0x2880, v4
	s_waitcnt vmcnt(22)
	ds_write2_b32 v125, v100, v101 offset0:8 offset1:73
	s_waitcnt vmcnt(20)
	ds_write2_b32 v125, v102, v103 offset0:138 offset1:203
	v_add_u32_e32 v125, 0x2c80, v4
	s_waitcnt vmcnt(18)
	ds_write2_b32 v125, v104, v105 offset0:12 offset1:77
	s_waitcnt vmcnt(16)
	ds_write2_b32 v125, v106, v107 offset0:142 offset1:207
	v_add_u32_e32 v125, 0x30c0, v4
	s_waitcnt vmcnt(14)
	ds_write2_b32 v125, v108, v109 offset1:65
	s_waitcnt vmcnt(12)
	ds_write2_b32 v125, v110, v111 offset0:130 offset1:195
	v_add_u32_e32 v125, 0x34c0, v4
	s_waitcnt vmcnt(10)
	ds_write2_b32 v125, v112, v113 offset0:4 offset1:69
	s_waitcnt vmcnt(8)
	ds_write2_b32 v125, v114, v115 offset0:134 offset1:199
	v_add_u32_e32 v125, 0x38c0, v4
	s_waitcnt vmcnt(6)
	ds_write2_b32 v125, v116, v117 offset0:8 offset1:73
	s_waitcnt vmcnt(4)
	ds_write2_b32 v125, v118, v119 offset0:138 offset1:203
	v_add_u32_e32 v125, 0x3cc0, v4
	s_waitcnt vmcnt(2)
	ds_write2_b32 v125, v120, v121 offset0:12 offset1:77
	s_waitcnt vmcnt(0)
	ds_write2_b32 v125, v122, v123 offset0:142 offset1:207
	v_add_u32_e32 v4, 0xffff7800, v1
	v_lshrrev_b32_e32 v25, 5, v4
	v_lshlrev_b32_e32 v27, 6, v4
	v_lshlrev_b32_e32 v29, 11, v25
	v_lshlrev_b32_e32 v4, 7, v25
	v_sub_u32_e32 v25, v27, v29
	s_waitcnt lgkmcnt(0)
	v_or_b32_e32 v60, v25, v39
	ds_read2_b32 v[34:35], v40 offset1:65
	v_ashrrev_i32_e32 v61, 31, v60
	s_waitcnt lgkmcnt(0)
	v_cvt_pk_bf16_f32 v34, v34, v35
	ds_read2_b32 v[36:37], v40 offset0:130 offset1:195
	v_add_u32_e32 v23, 0x400, v40
	v_lshl_add_u64 v[58:59], v[8:9], 0, v[4:5]
	v_lshlrev_b64 v[60:61], 13, v[60:61]
	s_waitcnt lgkmcnt(0)
	v_cvt_pk_bf16_f32 v35, v36, v37
	ds_read2_b32 v[36:37], v23 offset0:4 offset1:69
	v_lshl_add_u64 v[60:61], v[58:59], 0, v[60:61]
	s_waitcnt lgkmcnt(0)
	v_cvt_pk_bf16_f32 v36, v36, v37
	ds_read2_b32 v[56:57], v23 offset0:134 offset1:199
	s_waitcnt lgkmcnt(0)
	v_cvt_pk_bf16_f32 v37, v56, v57
	global_store_dwordx4 v[60:61], v[34:37], off
	v_or_b32_e32 v60, v25, v41
	v_ashrrev_i32_e32 v61, 31, v60
	ds_read2_b32 v[56:57], v40 offset0:8 offset1:73
	s_waitcnt lgkmcnt(0)
	v_cvt_pk_bf16_f32 v34, v56, v57
	ds_read2_b32 v[36:37], v40 offset0:138 offset1:203
	v_lshlrev_b64 v[60:61], 13, v[60:61]
	s_waitcnt lgkmcnt(0)
	v_cvt_pk_bf16_f32 v35, v36, v37
	ds_read2_b32 v[36:37], v23 offset0:12 offset1:77
	v_lshl_add_u64 v[60:61], v[58:59], 0, v[60:61]
	s_waitcnt lgkmcnt(0)
	v_cvt_pk_bf16_f32 v36, v36, v37
	ds_read2_b32 v[56:57], v23 offset0:142 offset1:207
	s_waitcnt lgkmcnt(0)
	v_cvt_pk_bf16_f32 v37, v56, v57
	global_store_dwordx4 v[60:61], v[34:37], off
	v_or_b32_e32 v60, v25, v42
	v_ashrrev_i32_e32 v61, 31, v60
	ds_read2_b32 v[56:57], v40 offset0:16 offset1:81
	s_waitcnt lgkmcnt(0)
	v_cvt_pk_bf16_f32 v34, v56, v57
	ds_read2_b32 v[36:37], v40 offset0:146 offset1:211
	v_lshlrev_b64 v[60:61], 13, v[60:61]
	s_waitcnt lgkmcnt(0)
	v_cvt_pk_bf16_f32 v35, v36, v37
	ds_read2_b32 v[36:37], v23 offset0:20 offset1:85
	v_lshl_add_u64 v[60:61], v[58:59], 0, v[60:61]
	s_waitcnt lgkmcnt(0)
	v_cvt_pk_bf16_f32 v36, v36, v37
	ds_read2_b32 v[56:57], v23 offset0:150 offset1:215
	s_waitcnt lgkmcnt(0)
	v_cvt_pk_bf16_f32 v37, v56, v57
	global_store_dwordx4 v[60:61], v[34:37], off
	v_or_b32_e32 v60, v25, v43
	v_ashrrev_i32_e32 v61, 31, v60
	ds_read2_b32 v[56:57], v40 offset0:24 offset1:89
	s_waitcnt lgkmcnt(0)
	v_cvt_pk_bf16_f32 v34, v56, v57
	ds_read2_b32 v[36:37], v40 offset0:154 offset1:219
	v_lshlrev_b64 v[60:61], 13, v[60:61]
	s_waitcnt lgkmcnt(0)
	v_cvt_pk_bf16_f32 v35, v36, v37
	ds_read2_b32 v[36:37], v23 offset0:28 offset1:93
	v_lshl_add_u64 v[60:61], v[58:59], 0, v[60:61]
	s_waitcnt lgkmcnt(0)
	v_cvt_pk_bf16_f32 v36, v36, v37
	ds_read2_b32 v[56:57], v23 offset0:158 offset1:223
	s_waitcnt lgkmcnt(0)
	v_cvt_pk_bf16_f32 v37, v56, v57
	global_store_dwordx4 v[60:61], v[34:37], off
	v_or_b32_e32 v60, v25, v44
	v_ashrrev_i32_e32 v61, 31, v60
	ds_read2_b32 v[56:57], v40 offset0:32 offset1:97
	s_waitcnt lgkmcnt(0)
	v_cvt_pk_bf16_f32 v34, v56, v57
	ds_read2_b32 v[36:37], v40 offset0:162 offset1:227
	v_lshlrev_b64 v[60:61], 13, v[60:61]
	s_waitcnt lgkmcnt(0)
	v_cvt_pk_bf16_f32 v35, v36, v37
	ds_read2_b32 v[36:37], v23 offset0:36 offset1:101
	v_lshl_add_u64 v[60:61], v[58:59], 0, v[60:61]
	s_waitcnt lgkmcnt(0)
	v_cvt_pk_bf16_f32 v36, v36, v37
	ds_read2_b32 v[56:57], v23 offset0:166 offset1:231
	s_waitcnt lgkmcnt(0)
	v_cvt_pk_bf16_f32 v37, v56, v57
	global_store_dwordx4 v[60:61], v[34:37], off
	v_or_b32_e32 v60, v25, v45
	v_ashrrev_i32_e32 v61, 31, v60
	ds_read2_b32 v[56:57], v40 offset0:40 offset1:105
	s_waitcnt lgkmcnt(0)
	v_cvt_pk_bf16_f32 v34, v56, v57
	ds_read2_b32 v[36:37], v40 offset0:170 offset1:235
	v_lshlrev_b64 v[60:61], 13, v[60:61]
	s_waitcnt lgkmcnt(0)
	v_cvt_pk_bf16_f32 v35, v36, v37
	ds_read2_b32 v[36:37], v23 offset0:44 offset1:109
	v_lshl_add_u64 v[60:61], v[58:59], 0, v[60:61]
	s_waitcnt lgkmcnt(0)
	v_cvt_pk_bf16_f32 v36, v36, v37
	ds_read2_b32 v[56:57], v23 offset0:174 offset1:239
	s_waitcnt lgkmcnt(0)
	v_cvt_pk_bf16_f32 v37, v56, v57
	global_store_dwordx4 v[60:61], v[34:37], off
	v_or_b32_e32 v60, v25, v46
	ds_read2_b32 v[56:57], v40 offset0:48 offset1:113
	s_waitcnt lgkmcnt(0)
	v_cvt_pk_bf16_f32 v34, v56, v57
	ds_read2_b32 v[36:37], v40 offset0:178 offset1:243
	v_ashrrev_i32_e32 v61, 31, v60
	s_waitcnt lgkmcnt(0)
	v_cvt_pk_bf16_f32 v35, v36, v37
	ds_read2_b32 v[36:37], v23 offset0:52 offset1:117
	v_lshlrev_b64 v[60:61], 13, v[60:61]
	s_waitcnt lgkmcnt(0)
	v_cvt_pk_bf16_f32 v36, v36, v37
	ds_read2_b32 v[56:57], v23 offset0:182 offset1:247
	s_waitcnt lgkmcnt(0)
	v_cvt_pk_bf16_f32 v37, v56, v57
	v_lshl_add_u64 v[60:61], v[58:59], 0, v[60:61]
	ds_read2_b32 v[56:57], v40 offset0:56 offset1:121
	global_store_dwordx4 v[60:61], v[34:37], off
	v_or_b32_e32 v60, v25, v47
	v_ashrrev_i32_e32 v61, 31, v60
	s_waitcnt lgkmcnt(0)
	v_cvt_pk_bf16_f32 v34, v56, v57
	ds_read2_b32 v[36:37], v40 offset0:186 offset1:251
	s_waitcnt lgkmcnt(0)
	v_cvt_pk_bf16_f32 v35, v36, v37
	ds_read2_b32 v[36:37], v23 offset0:60 offset1:125
	s_waitcnt lgkmcnt(0)
	v_cvt_pk_bf16_f32 v36, v36, v37
	ds_read2_b32 v[56:57], v23 offset0:190 offset1:255
	v_lshlrev_b64 v[60:61], 13, v[60:61]
	s_waitcnt lgkmcnt(0)
	v_cvt_pk_bf16_f32 v37, v56, v57
	v_lshl_add_u64 v[56:57], v[58:59], 0, v[60:61]
	global_store_dwordx4 v[56:57], v[34:37], off
	s_waitcnt lgkmcnt(0)

.LBB0_38:
	v_readfirstlane_b32 s20, v34
	v_readfirstlane_b32 s21, v35
	s_nop 4
	v_subrev_u32_e32 v124, s20, v34
	s_add_u32 s20, s20, 0x8000000
	s_addc_u32 s21, s21, 0
	global_load_dword v60, v124, s[20:21] nt
	s_add_u32 s20, s20, 0x10000
	s_addc_u32 s21, s21, 0
	global_load_dword v61, v124, s[20:21] nt
	s_add_u32 s20, s20, 0x10000
	s_addc_u32 s21, s21, 0
	global_load_dword v62, v124, s[20:21] nt
	s_add_u32 s20, s20, 0x10000
	s_addc_u32 s21, s21, 0
	global_load_dword v63, v124, s[20:21] nt
	s_add_u32 s20, s20, 0x10000
	s_addc_u32 s21, s21, 0
	global_load_dword v64, v124, s[20:21] nt
	s_add_u32 s20, s20, 0x10000
	s_addc_u32 s21, s21, 0
	global_load_dword v65, v124, s[20:21] nt
	s_add_u32 s20, s20, 0x10000
	s_addc_u32 s21, s21, 0
	global_load_dword v66, v124, s[20:21] nt
	s_add_u32 s20, s20, 0x10000
	s_addc_u32 s21, s21, 0
	global_load_dword v67, v124, s[20:21] nt
	s_add_u32 s20, s20, 0x10000
	s_addc_u32 s21, s21, 0
	global_load_dword v68, v124, s[20:21] nt
	s_add_u32 s20, s20, 0x10000
	s_addc_u32 s21, s21, 0
	global_load_dword v69, v124, s[20:21] nt
	s_add_u32 s20, s20, 0x10000
	s_addc_u32 s21, s21, 0
	global_load_dword v70, v124, s[20:21] nt
	s_add_u32 s20, s20, 0x10000
	s_addc_u32 s21, s21, 0
	global_load_dword v71, v124, s[20:21] nt
	s_add_u32 s20, s20, 0x10000
	s_addc_u32 s21, s21, 0
	global_load_dword v72, v124, s[20:21] nt
	s_add_u32 s20, s20, 0x10000
	s_addc_u32 s21, s21, 0
	global_load_dword v73, v124, s[20:21] nt
	s_add_u32 s20, s20, 0x10000
	s_addc_u32 s21, s21, 0
	global_load_dword v74, v124, s[20:21] nt
	s_add_u32 s20, s20, 0x10000
	s_addc_u32 s21, s21, 0
	global_load_dword v75, v124, s[20:21] nt
	s_add_u32 s20, s20, 0x10000
	s_addc_u32 s21, s21, 0
	global_load_dword v76, v124, s[20:21] nt
	s_add_u32 s20, s20, 0x10000
	s_addc_u32 s21, s21, 0
	global_load_dword v77, v124, s[20:21] nt
	s_add_u32 s20, s20, 0x10000
	s_addc_u32 s21, s21, 0
	global_load_dword v78, v124, s[20:21] nt
	s_add_u32 s20, s20, 0x10000
	s_addc_u32 s21, s21, 0
	global_load_dword v79, v124, s[20:21] nt
	s_add_u32 s20, s20, 0x10000
	s_addc_u32 s21, s21, 0
	global_load_dword v80, v124, s[20:21] nt
	s_add_u32 s20, s20, 0x10000
	s_addc_u32 s21, s21, 0
	global_load_dword v81, v124, s[20:21] nt
	s_add_u32 s20, s20, 0x10000
	s_addc_u32 s21, s21, 0
	global_load_dword v82, v124, s[20:21] nt
	s_add_u32 s20, s20, 0x10000
	s_addc_u32 s21, s21, 0
	global_load_dword v83, v124, s[20:21] nt
	s_add_u32 s20, s20, 0x10000
	s_addc_u32 s21, s21, 0
	global_load_dword v84, v124, s[20:21] nt
	s_add_u32 s20, s20, 0x10000
	s_addc_u32 s21, s21, 0
	global_load_dword v85, v124, s[20:21] nt
	s_add_u32 s20, s20, 0x10000
	s_addc_u32 s21, s21, 0
	global_load_dword v86, v124, s[20:21] nt
	s_add_u32 s20, s20, 0x10000
	s_addc_u32 s21, s21, 0
	global_load_dword v87, v124, s[20:21] nt
	s_add_u32 s20, s20, 0x10000
	s_addc_u32 s21, s21, 0
	global_load_dword v88, v124, s[20:21] nt
	s_add_u32 s20, s20, 0x10000
	s_addc_u32 s21, s21, 0
	global_load_dword v89, v124, s[20:21] nt
	s_add_u32 s20, s20, 0x10000
	s_addc_u32 s21, s21, 0
	global_load_dword v90, v124, s[20:21] nt
	s_add_u32 s20, s20, 0x10000
	s_addc_u32 s21, s21, 0
	global_load_dword v91, v124, s[20:21] nt
	s_add_u32 s20, s20, 0x10000
	s_addc_u32 s21, s21, 0
	global_load_dword v92, v124, s[20:21] nt
	s_add_u32 s20, s20, 0x10000
	s_addc_u32 s21, s21, 0
	global_load_dword v93, v124, s[20:21] nt
	s_add_u32 s20, s20, 0x10000
	s_addc_u32 s21, s21, 0
	global_load_dword v94, v124, s[20:21] nt
	s_add_u32 s20, s20, 0x10000
	s_addc_u32 s21, s21, 0
	global_load_dword v95, v124, s[20:21] nt
	s_add_u32 s20, s20, 0x10000
	s_addc_u32 s21, s21, 0
	global_load_dword v96, v124, s[20:21] nt
	s_add_u32 s20, s20, 0x10000
	s_addc_u32 s21, s21, 0
	global_load_dword v97, v124, s[20:21] nt
	s_add_u32 s20, s20, 0x10000
	s_addc_u32 s21, s21, 0
	global_load_dword v98, v124, s[20:21] nt
	s_add_u32 s20, s20, 0x10000
	s_addc_u32 s21, s21, 0
	global_load_dword v99, v124, s[20:21] nt
	s_add_u32 s20, s20, 0x10000
	s_addc_u32 s21, s21, 0
	global_load_dword v100, v124, s[20:21] nt
	s_add_u32 s20, s20, 0x10000
	s_addc_u32 s21, s21, 0
	global_load_dword v101, v124, s[20:21] nt
	s_add_u32 s20, s20, 0x10000
	s_addc_u32 s21, s21, 0
	global_load_dword v102, v124, s[20:21] nt
	s_add_u32 s20, s20, 0x10000
	s_addc_u32 s21, s21, 0
	global_load_dword v103, v124, s[20:21] nt
	s_add_u32 s20, s20, 0x10000
	s_addc_u32 s21, s21, 0
	global_load_dword v104, v124, s[20:21] nt
	s_add_u32 s20, s20, 0x10000
	s_addc_u32 s21, s21, 0
	global_load_dword v105, v124, s[20:21] nt
	s_add_u32 s20, s20, 0x10000
	s_addc_u32 s21, s21, 0
	global_load_dword v106, v124, s[20:21] nt
	s_add_u32 s20, s20, 0x10000
	s_addc_u32 s21, s21, 0
	global_load_dword v107, v124, s[20:21] nt
	s_add_u32 s20, s20, 0x10000
	s_addc_u32 s21, s21, 0
	global_load_dword v108, v124, s[20:21] nt
	s_add_u32 s20, s20, 0x10000
	s_addc_u32 s21, s21, 0
	global_load_dword v109, v124, s[20:21] nt
	s_add_u32 s20, s20, 0x10000
	s_addc_u32 s21, s21, 0
	global_load_dword v110, v124, s[20:21] nt
	s_add_u32 s20, s20, 0x10000
	s_addc_u32 s21, s21, 0
	global_load_dword v111, v124, s[20:21] nt
	s_add_u32 s20, s20, 0x10000
	s_addc_u32 s21, s21, 0
	global_load_dword v112, v124, s[20:21] nt
	s_add_u32 s20, s20, 0x10000
	s_addc_u32 s21, s21, 0
	global_load_dword v113, v124, s[20:21] nt
	s_add_u32 s20, s20, 0x10000
	s_addc_u32 s21, s21, 0
	global_load_dword v114, v124, s[20:21] nt
	s_add_u32 s20, s20, 0x10000
	s_addc_u32 s21, s21, 0
	global_load_dword v115, v124, s[20:21] nt
	s_add_u32 s20, s20, 0x10000
	s_addc_u32 s21, s21, 0
	global_load_dword v116, v124, s[20:21] nt
	s_add_u32 s20, s20, 0x10000
	s_addc_u32 s21, s21, 0
	global_load_dword v117, v124, s[20:21] nt
	s_add_u32 s20, s20, 0x10000
	s_addc_u32 s21, s21, 0
	global_load_dword v118, v124, s[20:21] nt
	s_add_u32 s20, s20, 0x10000
	s_addc_u32 s21, s21, 0
	global_load_dword v119, v124, s[20:21] nt
	s_add_u32 s20, s20, 0x10000
	s_addc_u32 s21, s21, 0
	global_load_dword v120, v124, s[20:21] nt
	s_add_u32 s20, s20, 0x10000
	s_addc_u32 s21, s21, 0
	global_load_dword v121, v124, s[20:21] nt
	s_add_u32 s20, s20, 0x10000
	s_addc_u32 s21, s21, 0
	global_load_dword v122, v124, s[20:21] nt
	s_add_u32 s20, s20, 0x10000
	s_addc_u32 s21, s21, 0
	global_load_dword v123, v124, s[20:21] nt
	s_waitcnt vmcnt(62)
	ds_write2_b32 v4, v60, v61 offset1:65
	s_waitcnt vmcnt(60)
	ds_write2_b32 v4, v62, v63 offset0:130 offset1:195
	v_add_u32_e32 v125, 0x400, v4
	s_waitcnt vmcnt(58)
	ds_write2_b32 v125, v64, v65 offset0:4 offset1:69
	s_waitcnt vmcnt(56)
	ds_write2_b32 v125, v66, v67 offset0:134 offset1:199
	v_add_u32_e32 v125, 0x800, v4
	s_waitcnt vmcnt(54)
	ds_write2_b32 v125, v68, v69 offset0:8 offset1:73
	s_waitcnt vmcnt(52)
	ds_write2_b32 v125, v70, v71 offset0:138 offset1:203
	v_add_u32_e32 v125, 0xc00, v4
	s_waitcnt vmcnt(50)
	ds_write2_b32 v125, v72, v73 offset0:12 offset1:77
	s_waitcnt vmcnt(48)
	ds_write2_b32 v125, v74, v75 offset0:142 offset1:207
	v_add_u32_e32 v125, 0x1040, v4
	s_waitcnt vmcnt(46)
	ds_write2_b32 v125, v76, v77 offset1:65
	s_waitcnt vmcnt(44)
	ds_write2_b32 v125, v78, v79 offset0:130 offset1:195
	v_add_u32_e32 v125, 0x1440, v4
	s_waitcnt vmcnt(42)
	ds_write2_b32 v125, v80, v81 offset0:4 offset1:69
	s_waitcnt vmcnt(40)
	ds_write2_b32 v125, v82, v83 offset0:134 offset1:199
	v_add_u32_e32 v125, 0x1840, v4
	s_waitcnt vmcnt(38)
	ds_write2_b32 v125, v84, v85 offset0:8 offset1:73
	s_waitcnt vmcnt(36)
	ds_write2_b32 v125, v86, v87 offset0:138 offset1:203
	v_add_u32_e32 v125, 0x1c40, v4
	s_waitcnt vmcnt(34)
	ds_write2_b32 v125, v88, v89 offset0:12 offset1:77
	s_waitcnt vmcnt(32)
	ds_write2_b32 v125, v90, v91 offset0:142 offset1:207
	v_add_u32_e32 v125, 0x2080, v4
	s_waitcnt vmcnt(30)
	ds_write2_b32 v125, v92, v93 offset1:65
	s_waitcnt vmcnt(28)
	ds_write2_b32 v125, v94, v95 offset0:130 offset1:195
	v_add_u32_e32 v125, 0x2480, v4
	s_waitcnt vmcnt(26)
	ds_write2_b32 v125, v96, v97 offset0:4 offset1:69
	s_waitcnt vmcnt(24)
	ds_write2_b32 v125, v98, v99 offset0:134 offset1:199
	v_add_u32_e32 v125, 0x2880, v4
	s_waitcnt vmcnt(22)
	ds_write2_b32 v125, v100, v101 offset0:8 offset1:73
	s_waitcnt vmcnt(20)
	ds_write2_b32 v125, v102, v103 offset0:138 offset1:203
	v_add_u32_e32 v125, 0x2c80, v4
	s_waitcnt vmcnt(18)
	ds_write2_b32 v125, v104, v105 offset0:12 offset1:77
	s_waitcnt vmcnt(16)
	ds_write2_b32 v125, v106, v107 offset0:142 offset1:207
	v_add_u32_e32 v125, 0x30c0, v4
	s_waitcnt vmcnt(14)
	ds_write2_b32 v125, v108, v109 offset1:65
	s_waitcnt vmcnt(12)
	ds_write2_b32 v125, v110, v111 offset0:130 offset1:195
	v_add_u32_e32 v125, 0x34c0, v4
	s_waitcnt vmcnt(10)
	ds_write2_b32 v125, v112, v113 offset0:4 offset1:69
	s_waitcnt vmcnt(8)
	ds_write2_b32 v125, v114, v115 offset0:134 offset1:199
	v_add_u32_e32 v125, 0x38c0, v4
	s_waitcnt vmcnt(6)
	ds_write2_b32 v125, v116, v117 offset0:8 offset1:73
	s_waitcnt vmcnt(4)
	ds_write2_b32 v125, v118, v119 offset0:138 offset1:203
	v_add_u32_e32 v125, 0x3cc0, v4
	s_waitcnt vmcnt(2)
	ds_write2_b32 v125, v120, v121 offset0:12 offset1:77
	s_waitcnt vmcnt(0)
	ds_write2_b32 v125, v122, v123 offset0:142 offset1:207
	v_add_u32_e32 v4, 0xffff9800, v1
	v_lshrrev_b32_e32 v25, 8, v4
	v_lshlrev_b32_e32 v27, 6, v4
	v_lshlrev_b32_e32 v29, 14, v25
	v_lshlrev_b32_e32 v4, 7, v25
	v_sub_u32_e32 v25, v27, v29
	s_waitcnt lgkmcnt(0)
	v_or_b32_e32 v60, v25, v39
	ds_read2_b32 v[34:35], v40 offset1:65
	v_ashrrev_i32_e32 v61, 31, v60
	s_waitcnt lgkmcnt(0)
	v_cvt_pk_bf16_f32 v34, v34, v35
	ds_read2_b32 v[36:37], v40 offset0:130 offset1:195
	v_add_u32_e32 v23, 0x400, v40
	v_lshl_add_u64 v[58:59], v[10:11], 0, v[4:5]
	v_lshlrev_b64 v[60:61], 12, v[60:61]
	s_waitcnt lgkmcnt(0)
	v_cvt_pk_bf16_f32 v35, v36, v37
	ds_read2_b32 v[36:37], v23 offset0:4 offset1:69
	v_lshl_add_u64 v[60:61], v[58:59], 0, v[60:61]
	s_waitcnt lgkmcnt(0)
	v_cvt_pk_bf16_f32 v36, v36, v37
	ds_read2_b32 v[56:57], v23 offset0:134 offset1:199
	s_waitcnt lgkmcnt(0)
	v_cvt_pk_bf16_f32 v37, v56, v57
	global_store_dwordx4 v[60:61], v[34:37], off
	v_or_b32_e32 v60, v25, v41
	v_ashrrev_i32_e32 v61, 31, v60
	ds_read2_b32 v[56:57], v40 offset0:8 offset1:73
	s_waitcnt lgkmcnt(0)
	v_cvt_pk_bf16_f32 v34, v56, v57
	ds_read2_b32 v[36:37], v40 offset0:138 offset1:203
	v_lshlrev_b64 v[60:61], 12, v[60:61]
	s_waitcnt lgkmcnt(0)
	v_cvt_pk_bf16_f32 v35, v36, v37
	ds_read2_b32 v[36:37], v23 offset0:12 offset1:77
	v_lshl_add_u64 v[60:61], v[58:59], 0, v[60:61]
	s_waitcnt lgkmcnt(0)
	v_cvt_pk_bf16_f32 v36, v36, v37
	ds_read2_b32 v[56:57], v23 offset0:142 offset1:207
	s_waitcnt lgkmcnt(0)
	v_cvt_pk_bf16_f32 v37, v56, v57
	global_store_dwordx4 v[60:61], v[34:37], off
	v_or_b32_e32 v60, v25, v42
	v_ashrrev_i32_e32 v61, 31, v60
	ds_read2_b32 v[56:57], v40 offset0:16 offset1:81
	s_waitcnt lgkmcnt(0)
	v_cvt_pk_bf16_f32 v34, v56, v57
	ds_read2_b32 v[36:37], v40 offset0:146 offset1:211
	v_lshlrev_b64 v[60:61], 12, v[60:61]
	s_waitcnt lgkmcnt(0)
	v_cvt_pk_bf16_f32 v35, v36, v37
	ds_read2_b32 v[36:37], v23 offset0:20 offset1:85
	v_lshl_add_u64 v[60:61], v[58:59], 0, v[60:61]
	s_waitcnt lgkmcnt(0)
	v_cvt_pk_bf16_f32 v36, v36, v37
	ds_read2_b32 v[56:57], v23 offset0:150 offset1:215
	s_waitcnt lgkmcnt(0)
	v_cvt_pk_bf16_f32 v37, v56, v57
	global_store_dwordx4 v[60:61], v[34:37], off
	v_or_b32_e32 v60, v25, v43
	v_ashrrev_i32_e32 v61, 31, v60
	ds_read2_b32 v[56:57], v40 offset0:24 offset1:89
	s_waitcnt lgkmcnt(0)
	v_cvt_pk_bf16_f32 v34, v56, v57
	ds_read2_b32 v[36:37], v40 offset0:154 offset1:219
	v_lshlrev_b64 v[60:61], 12, v[60:61]
	s_waitcnt lgkmcnt(0)
	v_cvt_pk_bf16_f32 v35, v36, v37
	ds_read2_b32 v[36:37], v23 offset0:28 offset1:93
	v_lshl_add_u64 v[60:61], v[58:59], 0, v[60:61]
	s_waitcnt lgkmcnt(0)
	v_cvt_pk_bf16_f32 v36, v36, v37
	ds_read2_b32 v[56:57], v23 offset0:158 offset1:223
	s_waitcnt lgkmcnt(0)
	v_cvt_pk_bf16_f32 v37, v56, v57
	global_store_dwordx4 v[60:61], v[34:37], off
	v_or_b32_e32 v60, v25, v44
	v_ashrrev_i32_e32 v61, 31, v60
	ds_read2_b32 v[56:57], v40 offset0:32 offset1:97
	s_waitcnt lgkmcnt(0)
	v_cvt_pk_bf16_f32 v34, v56, v57
	ds_read2_b32 v[36:37], v40 offset0:162 offset1:227
	v_lshlrev_b64 v[60:61], 12, v[60:61]
	s_waitcnt lgkmcnt(0)
	v_cvt_pk_bf16_f32 v35, v36, v37
	ds_read2_b32 v[36:37], v23 offset0:36 offset1:101
	v_lshl_add_u64 v[60:61], v[58:59], 0, v[60:61]
	s_waitcnt lgkmcnt(0)
	v_cvt_pk_bf16_f32 v36, v36, v37
	ds_read2_b32 v[56:57], v23 offset0:166 offset1:231
	s_waitcnt lgkmcnt(0)
	v_cvt_pk_bf16_f32 v37, v56, v57
	global_store_dwordx4 v[60:61], v[34:37], off
	v_or_b32_e32 v60, v25, v45
	v_ashrrev_i32_e32 v61, 31, v60
	ds_read2_b32 v[56:57], v40 offset0:40 offset1:105
	s_waitcnt lgkmcnt(0)
	v_cvt_pk_bf16_f32 v34, v56, v57
	ds_read2_b32 v[36:37], v40 offset0:170 offset1:235
	v_lshlrev_b64 v[60:61], 12, v[60:61]
	s_waitcnt lgkmcnt(0)
	v_cvt_pk_bf16_f32 v35, v36, v37
	ds_read2_b32 v[36:37], v23 offset0:44 offset1:109
	v_lshl_add_u64 v[60:61], v[58:59], 0, v[60:61]
	s_waitcnt lgkmcnt(0)
	v_cvt_pk_bf16_f32 v36, v36, v37
	ds_read2_b32 v[56:57], v23 offset0:174 offset1:239
	s_waitcnt lgkmcnt(0)
	v_cvt_pk_bf16_f32 v37, v56, v57
	global_store_dwordx4 v[60:61], v[34:37], off
	v_or_b32_e32 v60, v25, v46
	ds_read2_b32 v[56:57], v40 offset0:48 offset1:113
	s_waitcnt lgkmcnt(0)
	v_cvt_pk_bf16_f32 v34, v56, v57
	ds_read2_b32 v[36:37], v40 offset0:178 offset1:243
	v_ashrrev_i32_e32 v61, 31, v60
	s_waitcnt lgkmcnt(0)
	v_cvt_pk_bf16_f32 v35, v36, v37
	ds_read2_b32 v[36:37], v23 offset0:52 offset1:117
	v_lshlrev_b64 v[60:61], 12, v[60:61]
	s_waitcnt lgkmcnt(0)
	v_cvt_pk_bf16_f32 v36, v36, v37
	ds_read2_b32 v[56:57], v23 offset0:182 offset1:247
	s_waitcnt lgkmcnt(0)
	v_cvt_pk_bf16_f32 v37, v56, v57
	v_lshl_add_u64 v[60:61], v[58:59], 0, v[60:61]
	ds_read2_b32 v[56:57], v40 offset0:56 offset1:121
	global_store_dwordx4 v[60:61], v[34:37], off
	v_or_b32_e32 v60, v25, v47
	v_ashrrev_i32_e32 v61, 31, v60
	s_waitcnt lgkmcnt(0)
	v_cvt_pk_bf16_f32 v34, v56, v57
	ds_read2_b32 v[36:37], v40 offset0:186 offset1:251
	s_waitcnt lgkmcnt(0)
	v_cvt_pk_bf16_f32 v35, v36, v37
	ds_read2_b32 v[36:37], v23 offset0:60 offset1:125
	s_waitcnt lgkmcnt(0)
	v_cvt_pk_bf16_f32 v36, v36, v37
	ds_read2_b32 v[56:57], v23 offset0:190 offset1:255
	v_lshlrev_b64 v[60:61], 12, v[60:61]
	s_waitcnt lgkmcnt(0)
	v_cvt_pk_bf16_f32 v37, v56, v57
	v_lshl_add_u64 v[56:57], v[58:59], 0, v[60:61]
	global_store_dwordx4 v[56:57], v[34:37], off
	s_waitcnt lgkmcnt(0)

.LBB0_43:
	v_readfirstlane_b32 s18, v34
	v_readfirstlane_b32 s19, v35
	s_nop 4
	v_subrev_u32_e32 v124, s18, v34
	s_add_u32 s18, s18, 0x2000000
	s_addc_u32 s19, s19, 0
	global_load_dword v60, v124, s[18:19] nt
	s_add_u32 s18, s18, 0x2000
	s_addc_u32 s19, s19, 0
	global_load_dword v61, v124, s[18:19] nt
	s_add_u32 s18, s18, 0x2000
	s_addc_u32 s19, s19, 0
	global_load_dword v62, v124, s[18:19] nt
	s_add_u32 s18, s18, 0x2000
	s_addc_u32 s19, s19, 0
	global_load_dword v63, v124, s[18:19] nt
	s_add_u32 s18, s18, 0x2000
	s_addc_u32 s19, s19, 0
	global_load_dword v64, v124, s[18:19] nt
	s_add_u32 s18, s18, 0x2000
	s_addc_u32 s19, s19, 0
	global_load_dword v65, v124, s[18:19] nt
	s_add_u32 s18, s18, 0x2000
	s_addc_u32 s19, s19, 0
	global_load_dword v66, v124, s[18:19] nt
	s_add_u32 s18, s18, 0x2000
	s_addc_u32 s19, s19, 0
	global_load_dword v67, v124, s[18:19] nt
	s_add_u32 s18, s18, 0x2000
	s_addc_u32 s19, s19, 0
	global_load_dword v68, v124, s[18:19] nt
	s_add_u32 s18, s18, 0x2000
	s_addc_u32 s19, s19, 0
	global_load_dword v69, v124, s[18:19] nt
	s_add_u32 s18, s18, 0x2000
	s_addc_u32 s19, s19, 0
	global_load_dword v70, v124, s[18:19] nt
	s_add_u32 s18, s18, 0x2000
	s_addc_u32 s19, s19, 0
	global_load_dword v71, v124, s[18:19] nt
	s_add_u32 s18, s18, 0x2000
	s_addc_u32 s19, s19, 0
	global_load_dword v72, v124, s[18:19] nt
	s_add_u32 s18, s18, 0x2000
	s_addc_u32 s19, s19, 0
	global_load_dword v73, v124, s[18:19] nt
	s_add_u32 s18, s18, 0x2000
	s_addc_u32 s19, s19, 0
	global_load_dword v74, v124, s[18:19] nt
	s_add_u32 s18, s18, 0x2000
	s_addc_u32 s19, s19, 0
	global_load_dword v75, v124, s[18:19] nt
	s_add_u32 s18, s18, 0x2000
	s_addc_u32 s19, s19, 0
	global_load_dword v76, v124, s[18:19] nt
	s_add_u32 s18, s18, 0x2000
	s_addc_u32 s19, s19, 0
	global_load_dword v77, v124, s[18:19] nt
	s_add_u32 s18, s18, 0x2000
	s_addc_u32 s19, s19, 0
	global_load_dword v78, v124, s[18:19] nt
	s_add_u32 s18, s18, 0x2000
	s_addc_u32 s19, s19, 0
	global_load_dword v79, v124, s[18:19] nt
	s_add_u32 s18, s18, 0x2000
	s_addc_u32 s19, s19, 0
	global_load_dword v80, v124, s[18:19] nt
	s_add_u32 s18, s18, 0x2000
	s_addc_u32 s19, s19, 0
	global_load_dword v81, v124, s[18:19] nt
	s_add_u32 s18, s18, 0x2000
	s_addc_u32 s19, s19, 0
	global_load_dword v82, v124, s[18:19] nt
	s_add_u32 s18, s18, 0x2000
	s_addc_u32 s19, s19, 0
	global_load_dword v83, v124, s[18:19] nt
	s_add_u32 s18, s18, 0x2000
	s_addc_u32 s19, s19, 0
	global_load_dword v84, v124, s[18:19] nt
	s_add_u32 s18, s18, 0x2000
	s_addc_u32 s19, s19, 0
	global_load_dword v85, v124, s[18:19] nt
	s_add_u32 s18, s18, 0x2000
	s_addc_u32 s19, s19, 0
	global_load_dword v86, v124, s[18:19] nt
	s_add_u32 s18, s18, 0x2000
	s_addc_u32 s19, s19, 0
	global_load_dword v87, v124, s[18:19] nt
	s_add_u32 s18, s18, 0x2000
	s_addc_u32 s19, s19, 0
	global_load_dword v88, v124, s[18:19] nt
	s_add_u32 s18, s18, 0x2000
	s_addc_u32 s19, s19, 0
	global_load_dword v89, v124, s[18:19] nt
	s_add_u32 s18, s18, 0x2000
	s_addc_u32 s19, s19, 0
	global_load_dword v90, v124, s[18:19] nt
	s_add_u32 s18, s18, 0x2000
	s_addc_u32 s19, s19, 0
	global_load_dword v91, v124, s[18:19] nt
	s_add_u32 s18, s18, 0x2000
	s_addc_u32 s19, s19, 0
	global_load_dword v92, v124, s[18:19] nt
	s_add_u32 s18, s18, 0x2000
	s_addc_u32 s19, s19, 0
	global_load_dword v93, v124, s[18:19] nt
	s_add_u32 s18, s18, 0x2000
	s_addc_u32 s19, s19, 0
	global_load_dword v94, v124, s[18:19] nt
	s_add_u32 s18, s18, 0x2000
	s_addc_u32 s19, s19, 0
	global_load_dword v95, v124, s[18:19] nt
	s_add_u32 s18, s18, 0x2000
	s_addc_u32 s19, s19, 0
	global_load_dword v96, v124, s[18:19] nt
	s_add_u32 s18, s18, 0x2000
	s_addc_u32 s19, s19, 0
	global_load_dword v97, v124, s[18:19] nt
	s_add_u32 s18, s18, 0x2000
	s_addc_u32 s19, s19, 0
	global_load_dword v98, v124, s[18:19] nt
	s_add_u32 s18, s18, 0x2000
	s_addc_u32 s19, s19, 0
	global_load_dword v99, v124, s[18:19] nt
	s_add_u32 s18, s18, 0x2000
	s_addc_u32 s19, s19, 0
	global_load_dword v100, v124, s[18:19] nt
	s_add_u32 s18, s18, 0x2000
	s_addc_u32 s19, s19, 0
	global_load_dword v101, v124, s[18:19] nt
	s_add_u32 s18, s18, 0x2000
	s_addc_u32 s19, s19, 0
	global_load_dword v102, v124, s[18:19] nt
	s_add_u32 s18, s18, 0x2000
	s_addc_u32 s19, s19, 0
	global_load_dword v103, v124, s[18:19] nt
	s_add_u32 s18, s18, 0x2000
	s_addc_u32 s19, s19, 0
	global_load_dword v104, v124, s[18:19] nt
	s_add_u32 s18, s18, 0x2000
	s_addc_u32 s19, s19, 0
	global_load_dword v105, v124, s[18:19] nt
	s_add_u32 s18, s18, 0x2000
	s_addc_u32 s19, s19, 0
	global_load_dword v106, v124, s[18:19] nt
	s_add_u32 s18, s18, 0x2000
	s_addc_u32 s19, s19, 0
	global_load_dword v107, v124, s[18:19] nt
	s_add_u32 s18, s18, 0x2000
	s_addc_u32 s19, s19, 0
	global_load_dword v108, v124, s[18:19] nt
	s_add_u32 s18, s18, 0x2000
	s_addc_u32 s19, s19, 0
	global_load_dword v109, v124, s[18:19] nt
	s_add_u32 s18, s18, 0x2000
	s_addc_u32 s19, s19, 0
	global_load_dword v110, v124, s[18:19] nt
	s_add_u32 s18, s18, 0x2000
	s_addc_u32 s19, s19, 0
	global_load_dword v111, v124, s[18:19] nt
	s_add_u32 s18, s18, 0x2000
	s_addc_u32 s19, s19, 0
	global_load_dword v112, v124, s[18:19] nt
	s_add_u32 s18, s18, 0x2000
	s_addc_u32 s19, s19, 0
	global_load_dword v113, v124, s[18:19] nt
	s_add_u32 s18, s18, 0x2000
	s_addc_u32 s19, s19, 0
	global_load_dword v114, v124, s[18:19] nt
	s_add_u32 s18, s18, 0x2000
	s_addc_u32 s19, s19, 0
	global_load_dword v115, v124, s[18:19] nt
	s_add_u32 s18, s18, 0x2000
	s_addc_u32 s19, s19, 0
	global_load_dword v116, v124, s[18:19] nt
	s_add_u32 s18, s18, 0x2000
	s_addc_u32 s19, s19, 0
	global_load_dword v117, v124, s[18:19] nt
	s_add_u32 s18, s18, 0x2000
	s_addc_u32 s19, s19, 0
	global_load_dword v118, v124, s[18:19] nt
	s_add_u32 s18, s18, 0x2000
	s_addc_u32 s19, s19, 0
	global_load_dword v119, v124, s[18:19] nt
	s_add_u32 s18, s18, 0x2000
	s_addc_u32 s19, s19, 0
	global_load_dword v120, v124, s[18:19] nt
	s_add_u32 s18, s18, 0x2000
	s_addc_u32 s19, s19, 0
	global_load_dword v121, v124, s[18:19] nt
	s_add_u32 s18, s18, 0x2000
	s_addc_u32 s19, s19, 0
	global_load_dword v122, v124, s[18:19] nt
	s_add_u32 s18, s18, 0x2000
	s_addc_u32 s19, s19, 0
	global_load_dword v123, v124, s[18:19] nt
	s_waitcnt vmcnt(62)
	ds_write2_b32 v4, v60, v61 offset1:65
	s_waitcnt vmcnt(60)
	ds_write2_b32 v4, v62, v63 offset0:130 offset1:195
	v_add_u32_e32 v125, 0x400, v4
	s_waitcnt vmcnt(58)
	ds_write2_b32 v125, v64, v65 offset0:4 offset1:69
	s_waitcnt vmcnt(56)
	ds_write2_b32 v125, v66, v67 offset0:134 offset1:199
	v_add_u32_e32 v125, 0x800, v4
	s_waitcnt vmcnt(54)
	ds_write2_b32 v125, v68, v69 offset0:8 offset1:73
	s_waitcnt vmcnt(52)
	ds_write2_b32 v125, v70, v71 offset0:138 offset1:203
	v_add_u32_e32 v125, 0xc00, v4
	s_waitcnt vmcnt(50)
	ds_write2_b32 v125, v72, v73 offset0:12 offset1:77
	s_waitcnt vmcnt(48)
	ds_write2_b32 v125, v74, v75 offset0:142 offset1:207
	v_add_u32_e32 v125, 0x1040, v4
	s_waitcnt vmcnt(46)
	ds_write2_b32 v125, v76, v77 offset1:65
	s_waitcnt vmcnt(44)
	ds_write2_b32 v125, v78, v79 offset0:130 offset1:195
	v_add_u32_e32 v125, 0x1440, v4
	s_waitcnt vmcnt(42)
	ds_write2_b32 v125, v80, v81 offset0:4 offset1:69
	s_waitcnt vmcnt(40)
	ds_write2_b32 v125, v82, v83 offset0:134 offset1:199
	v_add_u32_e32 v125, 0x1840, v4
	s_waitcnt vmcnt(38)
	ds_write2_b32 v125, v84, v85 offset0:8 offset1:73
	s_waitcnt vmcnt(36)
	ds_write2_b32 v125, v86, v87 offset0:138 offset1:203
	v_add_u32_e32 v125, 0x1c40, v4
	s_waitcnt vmcnt(34)
	ds_write2_b32 v125, v88, v89 offset0:12 offset1:77
	s_waitcnt vmcnt(32)
	ds_write2_b32 v125, v90, v91 offset0:142 offset1:207
	v_add_u32_e32 v125, 0x2080, v4
	s_waitcnt vmcnt(30)
	ds_write2_b32 v125, v92, v93 offset1:65
	s_waitcnt vmcnt(28)
	ds_write2_b32 v125, v94, v95 offset0:130 offset1:195
	v_add_u32_e32 v125, 0x2480, v4
	s_waitcnt vmcnt(26)
	ds_write2_b32 v125, v96, v97 offset0:4 offset1:69
	s_waitcnt vmcnt(24)
	ds_write2_b32 v125, v98, v99 offset0:134 offset1:199
	v_add_u32_e32 v125, 0x2880, v4
	s_waitcnt vmcnt(22)
	ds_write2_b32 v125, v100, v101 offset0:8 offset1:73
	s_waitcnt vmcnt(20)
	ds_write2_b32 v125, v102, v103 offset0:138 offset1:203
	v_add_u32_e32 v125, 0x2c80, v4
	s_waitcnt vmcnt(18)
	ds_write2_b32 v125, v104, v105 offset0:12 offset1:77
	s_waitcnt vmcnt(16)
	ds_write2_b32 v125, v106, v107 offset0:142 offset1:207
	v_add_u32_e32 v125, 0x30c0, v4
	s_waitcnt vmcnt(14)
	ds_write2_b32 v125, v108, v109 offset1:65
	s_waitcnt vmcnt(12)
	ds_write2_b32 v125, v110, v111 offset0:130 offset1:195
	v_add_u32_e32 v125, 0x34c0, v4
	s_waitcnt vmcnt(10)
	ds_write2_b32 v125, v112, v113 offset0:4 offset1:69
	s_waitcnt vmcnt(8)
	ds_write2_b32 v125, v114, v115 offset0:134 offset1:199
	v_add_u32_e32 v125, 0x38c0, v4
	s_waitcnt vmcnt(6)
	ds_write2_b32 v125, v116, v117 offset0:8 offset1:73
	s_waitcnt vmcnt(4)
	ds_write2_b32 v125, v118, v119 offset0:138 offset1:203
	v_add_u32_e32 v125, 0x3cc0, v4
	s_waitcnt vmcnt(2)
	ds_write2_b32 v125, v120, v121 offset0:12 offset1:77
	s_waitcnt vmcnt(0)
	ds_write2_b32 v125, v122, v123 offset0:142 offset1:207
	v_add_u32_e32 v4, 0xffffa000, v1
	v_lshrrev_b32_e32 v25, 5, v4
	v_lshlrev_b32_e32 v27, 6, v4
	v_lshlrev_b32_e32 v29, 11, v25
	v_lshlrev_b32_e32 v4, 7, v25
	v_sub_u32_e32 v25, v27, v29
	s_waitcnt lgkmcnt(0)
	v_or_b32_e32 v60, v25, v39
	ds_read2_b32 v[34:35], v40 offset1:65
	v_ashrrev_i32_e32 v61, 31, v60
	s_waitcnt lgkmcnt(0)
	v_cvt_pk_bf16_f32 v34, v34, v35
	ds_read2_b32 v[36:37], v40 offset0:130 offset1:195
	v_add_u32_e32 v23, 0x400, v40
	v_lshl_add_u64 v[58:59], v[12:13], 0, v[4:5]
	v_lshlrev_b64 v[60:61], 13, v[60:61]
	s_waitcnt lgkmcnt(0)
	v_cvt_pk_bf16_f32 v35, v36, v37
	ds_read2_b32 v[36:37], v23 offset0:4 offset1:69
	v_lshl_add_u64 v[60:61], v[58:59], 0, v[60:61]
	s_waitcnt lgkmcnt(0)
	v_cvt_pk_bf16_f32 v36, v36, v37
	ds_read2_b32 v[56:57], v23 offset0:134 offset1:199
	s_waitcnt lgkmcnt(0)
	v_cvt_pk_bf16_f32 v37, v56, v57
	global_store_dwordx4 v[60:61], v[34:37], off
	v_or_b32_e32 v60, v25, v41
	v_ashrrev_i32_e32 v61, 31, v60
	ds_read2_b32 v[56:57], v40 offset0:8 offset1:73
	s_waitcnt lgkmcnt(0)
	v_cvt_pk_bf16_f32 v34, v56, v57
	ds_read2_b32 v[36:37], v40 offset0:138 offset1:203
	v_lshlrev_b64 v[60:61], 13, v[60:61]
	s_waitcnt lgkmcnt(0)
	v_cvt_pk_bf16_f32 v35, v36, v37
	ds_read2_b32 v[36:37], v23 offset0:12 offset1:77
	v_lshl_add_u64 v[60:61], v[58:59], 0, v[60:61]
	s_waitcnt lgkmcnt(0)
	v_cvt_pk_bf16_f32 v36, v36, v37
	ds_read2_b32 v[56:57], v23 offset0:142 offset1:207
	s_waitcnt lgkmcnt(0)
	v_cvt_pk_bf16_f32 v37, v56, v57
	global_store_dwordx4 v[60:61], v[34:37], off
	v_or_b32_e32 v60, v25, v42
	v_ashrrev_i32_e32 v61, 31, v60
	ds_read2_b32 v[56:57], v40 offset0:16 offset1:81
	s_waitcnt lgkmcnt(0)
	v_cvt_pk_bf16_f32 v34, v56, v57
	ds_read2_b32 v[36:37], v40 offset0:146 offset1:211
	v_lshlrev_b64 v[60:61], 13, v[60:61]
	s_waitcnt lgkmcnt(0)
	v_cvt_pk_bf16_f32 v35, v36, v37
	ds_read2_b32 v[36:37], v23 offset0:20 offset1:85
	v_lshl_add_u64 v[60:61], v[58:59], 0, v[60:61]
	s_waitcnt lgkmcnt(0)
	v_cvt_pk_bf16_f32 v36, v36, v37
	ds_read2_b32 v[56:57], v23 offset0:150 offset1:215
	s_waitcnt lgkmcnt(0)
	v_cvt_pk_bf16_f32 v37, v56, v57
	global_store_dwordx4 v[60:61], v[34:37], off
	v_or_b32_e32 v60, v25, v43
	v_ashrrev_i32_e32 v61, 31, v60
	ds_read2_b32 v[56:57], v40 offset0:24 offset1:89
	s_waitcnt lgkmcnt(0)
	v_cvt_pk_bf16_f32 v34, v56, v57
	ds_read2_b32 v[36:37], v40 offset0:154 offset1:219
	v_lshlrev_b64 v[60:61], 13, v[60:61]
	s_waitcnt lgkmcnt(0)
	v_cvt_pk_bf16_f32 v35, v36, v37
	ds_read2_b32 v[36:37], v23 offset0:28 offset1:93
	v_lshl_add_u64 v[60:61], v[58:59], 0, v[60:61]
	s_waitcnt lgkmcnt(0)
	v_cvt_pk_bf16_f32 v36, v36, v37
	ds_read2_b32 v[56:57], v23 offset0:158 offset1:223
	s_waitcnt lgkmcnt(0)
	v_cvt_pk_bf16_f32 v37, v56, v57
	global_store_dwordx4 v[60:61], v[34:37], off
	v_or_b32_e32 v60, v25, v44
	v_ashrrev_i32_e32 v61, 31, v60
	ds_read2_b32 v[56:57], v40 offset0:32 offset1:97
	s_waitcnt lgkmcnt(0)
	v_cvt_pk_bf16_f32 v34, v56, v57
	ds_read2_b32 v[36:37], v40 offset0:162 offset1:227
	v_lshlrev_b64 v[60:61], 13, v[60:61]
	s_waitcnt lgkmcnt(0)
	v_cvt_pk_bf16_f32 v35, v36, v37
	ds_read2_b32 v[36:37], v23 offset0:36 offset1:101
	v_lshl_add_u64 v[60:61], v[58:59], 0, v[60:61]
	s_waitcnt lgkmcnt(0)
	v_cvt_pk_bf16_f32 v36, v36, v37
	ds_read2_b32 v[56:57], v23 offset0:166 offset1:231
	s_waitcnt lgkmcnt(0)
	v_cvt_pk_bf16_f32 v37, v56, v57
	global_store_dwordx4 v[60:61], v[34:37], off
	v_or_b32_e32 v60, v25, v45
	v_ashrrev_i32_e32 v61, 31, v60
	ds_read2_b32 v[56:57], v40 offset0:40 offset1:105
	s_waitcnt lgkmcnt(0)
	v_cvt_pk_bf16_f32 v34, v56, v57
	ds_read2_b32 v[36:37], v40 offset0:170 offset1:235
	v_lshlrev_b64 v[60:61], 13, v[60:61]
	s_waitcnt lgkmcnt(0)
	v_cvt_pk_bf16_f32 v35, v36, v37
	ds_read2_b32 v[36:37], v23 offset0:44 offset1:109
	v_lshl_add_u64 v[60:61], v[58:59], 0, v[60:61]
	s_waitcnt lgkmcnt(0)
	v_cvt_pk_bf16_f32 v36, v36, v37
	ds_read2_b32 v[56:57], v23 offset0:174 offset1:239
	s_waitcnt lgkmcnt(0)
	v_cvt_pk_bf16_f32 v37, v56, v57
	global_store_dwordx4 v[60:61], v[34:37], off
	v_or_b32_e32 v60, v25, v46
	ds_read2_b32 v[56:57], v40 offset0:48 offset1:113
	s_waitcnt lgkmcnt(0)
	v_cvt_pk_bf16_f32 v34, v56, v57
	ds_read2_b32 v[36:37], v40 offset0:178 offset1:243
	v_ashrrev_i32_e32 v61, 31, v60
	s_waitcnt lgkmcnt(0)
	v_cvt_pk_bf16_f32 v35, v36, v37
	ds_read2_b32 v[36:37], v23 offset0:52 offset1:117
	v_lshlrev_b64 v[60:61], 13, v[60:61]
	s_waitcnt lgkmcnt(0)
	v_cvt_pk_bf16_f32 v36, v36, v37
	ds_read2_b32 v[56:57], v23 offset0:182 offset1:247
	s_waitcnt lgkmcnt(0)
	v_cvt_pk_bf16_f32 v37, v56, v57
	v_lshl_add_u64 v[60:61], v[58:59], 0, v[60:61]
	ds_read2_b32 v[56:57], v40 offset0:56 offset1:121
	global_store_dwordx4 v[60:61], v[34:37], off
	v_or_b32_e32 v60, v25, v47
	v_ashrrev_i32_e32 v61, 31, v60
	s_waitcnt lgkmcnt(0)
	v_cvt_pk_bf16_f32 v34, v56, v57
	ds_read2_b32 v[36:37], v40 offset0:186 offset1:251
	s_waitcnt lgkmcnt(0)
	v_cvt_pk_bf16_f32 v35, v36, v37
	ds_read2_b32 v[36:37], v23 offset0:60 offset1:125
	s_waitcnt lgkmcnt(0)
	v_cvt_pk_bf16_f32 v36, v36, v37
	ds_read2_b32 v[56:57], v23 offset0:190 offset1:255
	v_lshlrev_b64 v[60:61], 13, v[60:61]
	s_waitcnt lgkmcnt(0)
	v_cvt_pk_bf16_f32 v37, v56, v57
	v_lshl_add_u64 v[56:57], v[58:59], 0, v[60:61]
	global_store_dwordx4 v[56:57], v[34:37], off
	s_waitcnt lgkmcnt(0)

.LBB0_48:
	v_readfirstlane_b32 s16, v34
	v_readfirstlane_b32 s17, v35
	s_nop 4
	v_subrev_u32_e32 v124, s16, v34
	s_add_u32 s16, s16, 0x6000000
	s_addc_u32 s17, s17, 0
	global_load_dword v60, v124, s[16:17] nt
	s_add_u32 s16, s16, 0xc000
	s_addc_u32 s17, s17, 0
	global_load_dword v61, v124, s[16:17] nt
	s_add_u32 s16, s16, 0xc000
	s_addc_u32 s17, s17, 0
	global_load_dword v62, v124, s[16:17] nt
	s_add_u32 s16, s16, 0xc000
	s_addc_u32 s17, s17, 0
	global_load_dword v63, v124, s[16:17] nt
	s_add_u32 s16, s16, 0xc000
	s_addc_u32 s17, s17, 0
	global_load_dword v64, v124, s[16:17] nt
	s_add_u32 s16, s16, 0xc000
	s_addc_u32 s17, s17, 0
	global_load_dword v65, v124, s[16:17] nt
	s_add_u32 s16, s16, 0xc000
	s_addc_u32 s17, s17, 0
	global_load_dword v66, v124, s[16:17] nt
	s_add_u32 s16, s16, 0xc000
	s_addc_u32 s17, s17, 0
	global_load_dword v67, v124, s[16:17] nt
	s_add_u32 s16, s16, 0xc000
	s_addc_u32 s17, s17, 0
	global_load_dword v68, v124, s[16:17] nt
	s_add_u32 s16, s16, 0xc000
	s_addc_u32 s17, s17, 0
	global_load_dword v69, v124, s[16:17] nt
	s_add_u32 s16, s16, 0xc000
	s_addc_u32 s17, s17, 0
	global_load_dword v70, v124, s[16:17] nt
	s_add_u32 s16, s16, 0xc000
	s_addc_u32 s17, s17, 0
	global_load_dword v71, v124, s[16:17] nt
	s_add_u32 s16, s16, 0xc000
	s_addc_u32 s17, s17, 0
	global_load_dword v72, v124, s[16:17] nt
	s_add_u32 s16, s16, 0xc000
	s_addc_u32 s17, s17, 0
	global_load_dword v73, v124, s[16:17] nt
	s_add_u32 s16, s16, 0xc000
	s_addc_u32 s17, s17, 0
	global_load_dword v74, v124, s[16:17] nt
	s_add_u32 s16, s16, 0xc000
	s_addc_u32 s17, s17, 0
	global_load_dword v75, v124, s[16:17] nt
	s_add_u32 s16, s16, 0xc000
	s_addc_u32 s17, s17, 0
	global_load_dword v76, v124, s[16:17] nt
	s_add_u32 s16, s16, 0xc000
	s_addc_u32 s17, s17, 0
	global_load_dword v77, v124, s[16:17] nt
	s_add_u32 s16, s16, 0xc000
	s_addc_u32 s17, s17, 0
	global_load_dword v78, v124, s[16:17] nt
	s_add_u32 s16, s16, 0xc000
	s_addc_u32 s17, s17, 0
	global_load_dword v79, v124, s[16:17] nt
	s_add_u32 s16, s16, 0xc000
	s_addc_u32 s17, s17, 0
	global_load_dword v80, v124, s[16:17] nt
	s_add_u32 s16, s16, 0xc000
	s_addc_u32 s17, s17, 0
	global_load_dword v81, v124, s[16:17] nt
	s_add_u32 s16, s16, 0xc000
	s_addc_u32 s17, s17, 0
	global_load_dword v82, v124, s[16:17] nt
	s_add_u32 s16, s16, 0xc000
	s_addc_u32 s17, s17, 0
	global_load_dword v83, v124, s[16:17] nt
	s_add_u32 s16, s16, 0xc000
	s_addc_u32 s17, s17, 0
	global_load_dword v84, v124, s[16:17] nt
	s_add_u32 s16, s16, 0xc000
	s_addc_u32 s17, s17, 0
	global_load_dword v85, v124, s[16:17] nt
	s_add_u32 s16, s16, 0xc000
	s_addc_u32 s17, s17, 0
	global_load_dword v86, v124, s[16:17] nt
	s_add_u32 s16, s16, 0xc000
	s_addc_u32 s17, s17, 0
	global_load_dword v87, v124, s[16:17] nt
	s_add_u32 s16, s16, 0xc000
	s_addc_u32 s17, s17, 0
	global_load_dword v88, v124, s[16:17] nt
	s_add_u32 s16, s16, 0xc000
	s_addc_u32 s17, s17, 0
	global_load_dword v89, v124, s[16:17] nt
	s_add_u32 s16, s16, 0xc000
	s_addc_u32 s17, s17, 0
	global_load_dword v90, v124, s[16:17] nt
	s_add_u32 s16, s16, 0xc000
	s_addc_u32 s17, s17, 0
	global_load_dword v91, v124, s[16:17] nt
	s_add_u32 s16, s16, 0xc000
	s_addc_u32 s17, s17, 0
	global_load_dword v92, v124, s[16:17] nt
	s_add_u32 s16, s16, 0xc000
	s_addc_u32 s17, s17, 0
	global_load_dword v93, v124, s[16:17] nt
	s_add_u32 s16, s16, 0xc000
	s_addc_u32 s17, s17, 0
	global_load_dword v94, v124, s[16:17] nt
	s_add_u32 s16, s16, 0xc000
	s_addc_u32 s17, s17, 0
	global_load_dword v95, v124, s[16:17] nt
	s_add_u32 s16, s16, 0xc000
	s_addc_u32 s17, s17, 0
	global_load_dword v96, v124, s[16:17] nt
	s_add_u32 s16, s16, 0xc000
	s_addc_u32 s17, s17, 0
	global_load_dword v97, v124, s[16:17] nt
	s_add_u32 s16, s16, 0xc000
	s_addc_u32 s17, s17, 0
	global_load_dword v98, v124, s[16:17] nt
	s_add_u32 s16, s16, 0xc000
	s_addc_u32 s17, s17, 0
	global_load_dword v99, v124, s[16:17] nt
	s_add_u32 s16, s16, 0xc000
	s_addc_u32 s17, s17, 0
	global_load_dword v100, v124, s[16:17] nt
	s_add_u32 s16, s16, 0xc000
	s_addc_u32 s17, s17, 0
	global_load_dword v101, v124, s[16:17] nt
	s_add_u32 s16, s16, 0xc000
	s_addc_u32 s17, s17, 0
	global_load_dword v102, v124, s[16:17] nt
	s_add_u32 s16, s16, 0xc000
	s_addc_u32 s17, s17, 0
	global_load_dword v103, v124, s[16:17] nt
	s_add_u32 s16, s16, 0xc000
	s_addc_u32 s17, s17, 0
	global_load_dword v104, v124, s[16:17] nt
	s_add_u32 s16, s16, 0xc000
	s_addc_u32 s17, s17, 0
	global_load_dword v105, v124, s[16:17] nt
	s_add_u32 s16, s16, 0xc000
	s_addc_u32 s17, s17, 0
	global_load_dword v106, v124, s[16:17] nt
	s_add_u32 s16, s16, 0xc000
	s_addc_u32 s17, s17, 0
	global_load_dword v107, v124, s[16:17] nt
	s_add_u32 s16, s16, 0xc000
	s_addc_u32 s17, s17, 0
	global_load_dword v108, v124, s[16:17] nt
	s_add_u32 s16, s16, 0xc000
	s_addc_u32 s17, s17, 0
	global_load_dword v109, v124, s[16:17] nt
	s_add_u32 s16, s16, 0xc000
	s_addc_u32 s17, s17, 0
	global_load_dword v110, v124, s[16:17] nt
	s_add_u32 s16, s16, 0xc000
	s_addc_u32 s17, s17, 0
	global_load_dword v111, v124, s[16:17] nt
	s_add_u32 s16, s16, 0xc000
	s_addc_u32 s17, s17, 0
	global_load_dword v112, v124, s[16:17] nt
	s_add_u32 s16, s16, 0xc000
	s_addc_u32 s17, s17, 0
	global_load_dword v113, v124, s[16:17] nt
	s_add_u32 s16, s16, 0xc000
	s_addc_u32 s17, s17, 0
	global_load_dword v114, v124, s[16:17] nt
	s_add_u32 s16, s16, 0xc000
	s_addc_u32 s17, s17, 0
	global_load_dword v115, v124, s[16:17] nt
	s_add_u32 s16, s16, 0xc000
	s_addc_u32 s17, s17, 0
	global_load_dword v116, v124, s[16:17] nt
	s_add_u32 s16, s16, 0xc000
	s_addc_u32 s17, s17, 0
	global_load_dword v117, v124, s[16:17] nt
	s_add_u32 s16, s16, 0xc000
	s_addc_u32 s17, s17, 0
	global_load_dword v118, v124, s[16:17] nt
	s_add_u32 s16, s16, 0xc000
	s_addc_u32 s17, s17, 0
	global_load_dword v119, v124, s[16:17] nt
	s_add_u32 s16, s16, 0xc000
	s_addc_u32 s17, s17, 0
	global_load_dword v120, v124, s[16:17] nt
	s_add_u32 s16, s16, 0xc000
	s_addc_u32 s17, s17, 0
	global_load_dword v121, v124, s[16:17] nt
	s_add_u32 s16, s16, 0xc000
	s_addc_u32 s17, s17, 0
	global_load_dword v122, v124, s[16:17] nt
	s_add_u32 s16, s16, 0xc000
	s_addc_u32 s17, s17, 0
	global_load_dword v123, v124, s[16:17] nt
	s_waitcnt vmcnt(62)
	ds_write2_b32 v27, v60, v61 offset1:65
	s_waitcnt vmcnt(60)
	ds_write2_b32 v27, v62, v63 offset0:130 offset1:195
	v_add_u32_e32 v125, 0x400, v27
	s_waitcnt vmcnt(58)
	ds_write2_b32 v125, v64, v65 offset0:4 offset1:69
	s_waitcnt vmcnt(56)
	ds_write2_b32 v125, v66, v67 offset0:134 offset1:199
	v_add_u32_e32 v125, 0x800, v27
	s_waitcnt vmcnt(54)
	ds_write2_b32 v125, v68, v69 offset0:8 offset1:73
	s_waitcnt vmcnt(52)
	ds_write2_b32 v125, v70, v71 offset0:138 offset1:203
	v_add_u32_e32 v125, 0xc00, v27
	s_waitcnt vmcnt(50)
	ds_write2_b32 v125, v72, v73 offset0:12 offset1:77
	s_waitcnt vmcnt(48)
	ds_write2_b32 v125, v74, v75 offset0:142 offset1:207
	v_add_u32_e32 v125, 0x1040, v27
	s_waitcnt vmcnt(46)
	ds_write2_b32 v125, v76, v77 offset1:65
	s_waitcnt vmcnt(44)
	ds_write2_b32 v125, v78, v79 offset0:130 offset1:195
	v_add_u32_e32 v125, 0x1440, v27
	s_waitcnt vmcnt(42)
	ds_write2_b32 v125, v80, v81 offset0:4 offset1:69
	s_waitcnt vmcnt(40)
	ds_write2_b32 v125, v82, v83 offset0:134 offset1:199
	v_add_u32_e32 v125, 0x1840, v27
	s_waitcnt vmcnt(38)
	ds_write2_b32 v125, v84, v85 offset0:8 offset1:73
	s_waitcnt vmcnt(36)
	ds_write2_b32 v125, v86, v87 offset0:138 offset1:203
	v_add_u32_e32 v125, 0x1c40, v27
	s_waitcnt vmcnt(34)
	ds_write2_b32 v125, v88, v89 offset0:12 offset1:77
	s_waitcnt vmcnt(32)
	ds_write2_b32 v125, v90, v91 offset0:142 offset1:207
	v_add_u32_e32 v125, 0x2080, v27
	s_waitcnt vmcnt(30)
	ds_write2_b32 v125, v92, v93 offset1:65
	s_waitcnt vmcnt(28)
	ds_write2_b32 v125, v94, v95 offset0:130 offset1:195
	v_add_u32_e32 v125, 0x2480, v27
	s_waitcnt vmcnt(26)
	ds_write2_b32 v125, v96, v97 offset0:4 offset1:69
	s_waitcnt vmcnt(24)
	ds_write2_b32 v125, v98, v99 offset0:134 offset1:199
	v_add_u32_e32 v125, 0x2880, v27
	s_waitcnt vmcnt(22)
	ds_write2_b32 v125, v100, v101 offset0:8 offset1:73
	s_waitcnt vmcnt(20)
	ds_write2_b32 v125, v102, v103 offset0:138 offset1:203
	v_add_u32_e32 v125, 0x2c80, v27
	s_waitcnt vmcnt(18)
	ds_write2_b32 v125, v104, v105 offset0:12 offset1:77
	s_waitcnt vmcnt(16)
	ds_write2_b32 v125, v106, v107 offset0:142 offset1:207
	v_add_u32_e32 v125, 0x30c0, v27
	s_waitcnt vmcnt(14)
	ds_write2_b32 v125, v108, v109 offset1:65
	s_waitcnt vmcnt(12)
	ds_write2_b32 v125, v110, v111 offset0:130 offset1:195
	v_add_u32_e32 v125, 0x34c0, v27
	s_waitcnt vmcnt(10)
	ds_write2_b32 v125, v112, v113 offset0:4 offset1:69
	s_waitcnt vmcnt(8)
	ds_write2_b32 v125, v114, v115 offset0:134 offset1:199
	v_add_u32_e32 v125, 0x38c0, v27
	s_waitcnt vmcnt(6)
	ds_write2_b32 v125, v116, v117 offset0:8 offset1:73
	s_waitcnt vmcnt(4)
	ds_write2_b32 v125, v118, v119 offset0:138 offset1:203
	v_add_u32_e32 v125, 0x3cc0, v27
	s_waitcnt vmcnt(2)
	ds_write2_b32 v125, v120, v121 offset0:12 offset1:77
	s_waitcnt vmcnt(0)
	ds_write2_b32 v125, v122, v123 offset0:142 offset1:207
	v_add_lshl_u32 v23, v23, v4, 6
	s_waitcnt lgkmcnt(0)
	v_or_b32_e32 v60, v23, v39
	ds_read2_b32 v[34:35], v40 offset1:65
	v_lshlrev_b32_e32 v4, 1, v25
	v_ashrrev_i32_e32 v61, 31, v60
	s_waitcnt lgkmcnt(0)
	v_cvt_pk_bf16_f32 v34, v34, v35
	ds_read2_b32 v[36:37], v40 offset0:130 offset1:195
	v_add_u32_e32 v27, 0x400, v40
	v_lshl_add_u64 v[58:59], v[14:15], 0, v[4:5]
	v_lshlrev_b64 v[60:61], 12, v[60:61]
	s_waitcnt lgkmcnt(0)
	v_cvt_pk_bf16_f32 v35, v36, v37
	ds_read2_b32 v[36:37], v27 offset0:4 offset1:69
	v_lshl_add_u64 v[60:61], v[58:59], 0, v[60:61]
	s_waitcnt lgkmcnt(0)
	v_cvt_pk_bf16_f32 v36, v36, v37
	ds_read2_b32 v[56:57], v27 offset0:134 offset1:199
	s_waitcnt lgkmcnt(0)
	v_cvt_pk_bf16_f32 v37, v56, v57
	global_store_dwordx4 v[60:61], v[34:37], off
	v_or_b32_e32 v60, v23, v41
	v_ashrrev_i32_e32 v61, 31, v60
	ds_read2_b32 v[56:57], v40 offset0:8 offset1:73
	s_waitcnt lgkmcnt(0)
	v_cvt_pk_bf16_f32 v34, v56, v57
	ds_read2_b32 v[36:37], v40 offset0:138 offset1:203
	v_lshlrev_b64 v[60:61], 12, v[60:61]
	s_waitcnt lgkmcnt(0)
	v_cvt_pk_bf16_f32 v35, v36, v37
	ds_read2_b32 v[36:37], v27 offset0:12 offset1:77
	v_lshl_add_u64 v[60:61], v[58:59], 0, v[60:61]
	s_waitcnt lgkmcnt(0)
	v_cvt_pk_bf16_f32 v36, v36, v37
	ds_read2_b32 v[56:57], v27 offset0:142 offset1:207
	s_waitcnt lgkmcnt(0)
	v_cvt_pk_bf16_f32 v37, v56, v57
	global_store_dwordx4 v[60:61], v[34:37], off
	v_or_b32_e32 v60, v23, v42
	v_ashrrev_i32_e32 v61, 31, v60
	ds_read2_b32 v[56:57], v40 offset0:16 offset1:81
	s_waitcnt lgkmcnt(0)
	v_cvt_pk_bf16_f32 v34, v56, v57
	ds_read2_b32 v[36:37], v40 offset0:146 offset1:211
	v_lshlrev_b64 v[60:61], 12, v[60:61]
	s_waitcnt lgkmcnt(0)
	v_cvt_pk_bf16_f32 v35, v36, v37
	ds_read2_b32 v[36:37], v27 offset0:20 offset1:85
	v_lshl_add_u64 v[60:61], v[58:59], 0, v[60:61]
	s_waitcnt lgkmcnt(0)
	v_cvt_pk_bf16_f32 v36, v36, v37
	ds_read2_b32 v[56:57], v27 offset0:150 offset1:215
	s_waitcnt lgkmcnt(0)
	v_cvt_pk_bf16_f32 v37, v56, v57
	global_store_dwordx4 v[60:61], v[34:37], off
	v_or_b32_e32 v60, v23, v43
	v_ashrrev_i32_e32 v61, 31, v60
	ds_read2_b32 v[56:57], v40 offset0:24 offset1:89
	s_waitcnt lgkmcnt(0)
	v_cvt_pk_bf16_f32 v34, v56, v57
	ds_read2_b32 v[36:37], v40 offset0:154 offset1:219
	v_lshlrev_b64 v[60:61], 12, v[60:61]
	s_waitcnt lgkmcnt(0)
	v_cvt_pk_bf16_f32 v35, v36, v37
	ds_read2_b32 v[36:37], v27 offset0:28 offset1:93
	v_lshl_add_u64 v[60:61], v[58:59], 0, v[60:61]
	s_waitcnt lgkmcnt(0)
	v_cvt_pk_bf16_f32 v36, v36, v37
	ds_read2_b32 v[56:57], v27 offset0:158 offset1:223
	s_waitcnt lgkmcnt(0)
	v_cvt_pk_bf16_f32 v37, v56, v57
	global_store_dwordx4 v[60:61], v[34:37], off
	v_or_b32_e32 v60, v23, v44
	v_ashrrev_i32_e32 v61, 31, v60
	ds_read2_b32 v[56:57], v40 offset0:32 offset1:97
	s_waitcnt lgkmcnt(0)
	v_cvt_pk_bf16_f32 v34, v56, v57
	ds_read2_b32 v[36:37], v40 offset0:162 offset1:227
	v_lshlrev_b64 v[60:61], 12, v[60:61]
	s_waitcnt lgkmcnt(0)
	v_cvt_pk_bf16_f32 v35, v36, v37
	ds_read2_b32 v[36:37], v27 offset0:36 offset1:101
	v_lshl_add_u64 v[60:61], v[58:59], 0, v[60:61]
	s_waitcnt lgkmcnt(0)
	v_cvt_pk_bf16_f32 v36, v36, v37
	ds_read2_b32 v[56:57], v27 offset0:166 offset1:231
	s_waitcnt lgkmcnt(0)
	v_cvt_pk_bf16_f32 v37, v56, v57
	global_store_dwordx4 v[60:61], v[34:37], off
	v_or_b32_e32 v60, v23, v45
	v_ashrrev_i32_e32 v61, 31, v60
	ds_read2_b32 v[56:57], v40 offset0:40 offset1:105
	s_waitcnt lgkmcnt(0)
	v_cvt_pk_bf16_f32 v34, v56, v57
	ds_read2_b32 v[36:37], v40 offset0:170 offset1:235
	v_lshlrev_b64 v[60:61], 12, v[60:61]
	s_waitcnt lgkmcnt(0)
	v_cvt_pk_bf16_f32 v35, v36, v37
	ds_read2_b32 v[36:37], v27 offset0:44 offset1:109
	v_lshl_add_u64 v[60:61], v[58:59], 0, v[60:61]
	s_waitcnt lgkmcnt(0)
	v_cvt_pk_bf16_f32 v36, v36, v37
	ds_read2_b32 v[56:57], v27 offset0:174 offset1:239
	s_waitcnt lgkmcnt(0)
	v_cvt_pk_bf16_f32 v37, v56, v57
	global_store_dwordx4 v[60:61], v[34:37], off
	v_or_b32_e32 v60, v23, v46
	ds_read2_b32 v[56:57], v40 offset0:48 offset1:113
	s_waitcnt lgkmcnt(0)
	v_cvt_pk_bf16_f32 v34, v56, v57
	ds_read2_b32 v[36:37], v40 offset0:178 offset1:243
	v_ashrrev_i32_e32 v61, 31, v60
	s_waitcnt lgkmcnt(0)
	v_cvt_pk_bf16_f32 v35, v36, v37
	ds_read2_b32 v[36:37], v27 offset0:52 offset1:117
	v_lshlrev_b64 v[60:61], 12, v[60:61]
	s_waitcnt lgkmcnt(0)
	v_cvt_pk_bf16_f32 v36, v36, v37
	ds_read2_b32 v[56:57], v27 offset0:182 offset1:247
	s_waitcnt lgkmcnt(0)
	v_cvt_pk_bf16_f32 v37, v56, v57
	v_lshl_add_u64 v[60:61], v[58:59], 0, v[60:61]
	ds_read2_b32 v[56:57], v40 offset0:56 offset1:121
	global_store_dwordx4 v[60:61], v[34:37], off
	v_or_b32_e32 v60, v23, v47
	v_ashrrev_i32_e32 v61, 31, v60
	s_waitcnt lgkmcnt(0)
	v_cvt_pk_bf16_f32 v34, v56, v57
	ds_read2_b32 v[36:37], v40 offset0:186 offset1:251
	s_waitcnt lgkmcnt(0)
	v_cvt_pk_bf16_f32 v35, v36, v37
	ds_read2_b32 v[36:37], v27 offset0:60 offset1:125
	s_waitcnt lgkmcnt(0)
	v_cvt_pk_bf16_f32 v36, v36, v37
	ds_read2_b32 v[56:57], v27 offset0:190 offset1:255
	v_lshlrev_b64 v[60:61], 12, v[60:61]
	s_waitcnt lgkmcnt(0)
	v_cvt_pk_bf16_f32 v37, v56, v57
	v_lshl_add_u64 v[56:57], v[58:59], 0, v[60:61]
	global_store_dwordx4 v[56:57], v[34:37], off
	s_waitcnt lgkmcnt(0)

.LBB0_53:
	v_readfirstlane_b32 s14, v34
	v_readfirstlane_b32 s15, v35
	s_nop 4
	v_subrev_u32_e32 v124, s14, v34
	global_load_dword v60, v124, s[14:15] nt
	s_add_u32 s14, s14, 0x2000
	s_addc_u32 s15, s15, 0
	global_load_dword v61, v124, s[14:15] nt
	s_add_u32 s14, s14, 0x2000
	s_addc_u32 s15, s15, 0
	global_load_dword v62, v124, s[14:15] nt
	s_add_u32 s14, s14, 0x2000
	s_addc_u32 s15, s15, 0
	global_load_dword v63, v124, s[14:15] nt
	s_add_u32 s14, s14, 0x2000
	s_addc_u32 s15, s15, 0
	global_load_dword v64, v124, s[14:15] nt
	s_add_u32 s14, s14, 0x2000
	s_addc_u32 s15, s15, 0
	global_load_dword v65, v124, s[14:15] nt
	s_add_u32 s14, s14, 0x2000
	s_addc_u32 s15, s15, 0
	global_load_dword v66, v124, s[14:15] nt
	s_add_u32 s14, s14, 0x2000
	s_addc_u32 s15, s15, 0
	global_load_dword v67, v124, s[14:15] nt
	s_add_u32 s14, s14, 0x2000
	s_addc_u32 s15, s15, 0
	global_load_dword v68, v124, s[14:15] nt
	s_add_u32 s14, s14, 0x2000
	s_addc_u32 s15, s15, 0
	global_load_dword v69, v124, s[14:15] nt
	s_add_u32 s14, s14, 0x2000
	s_addc_u32 s15, s15, 0
	global_load_dword v70, v124, s[14:15] nt
	s_add_u32 s14, s14, 0x2000
	s_addc_u32 s15, s15, 0
	global_load_dword v71, v124, s[14:15] nt
	s_add_u32 s14, s14, 0x2000
	s_addc_u32 s15, s15, 0
	global_load_dword v72, v124, s[14:15] nt
	s_add_u32 s14, s14, 0x2000
	s_addc_u32 s15, s15, 0
	global_load_dword v73, v124, s[14:15] nt
	s_add_u32 s14, s14, 0x2000
	s_addc_u32 s15, s15, 0
	global_load_dword v74, v124, s[14:15] nt
	s_add_u32 s14, s14, 0x2000
	s_addc_u32 s15, s15, 0
	global_load_dword v75, v124, s[14:15] nt
	s_add_u32 s14, s14, 0x2000
	s_addc_u32 s15, s15, 0
	global_load_dword v76, v124, s[14:15] nt
	s_add_u32 s14, s14, 0x2000
	s_addc_u32 s15, s15, 0
	global_load_dword v77, v124, s[14:15] nt
	s_add_u32 s14, s14, 0x2000
	s_addc_u32 s15, s15, 0
	global_load_dword v78, v124, s[14:15] nt
	s_add_u32 s14, s14, 0x2000
	s_addc_u32 s15, s15, 0
	global_load_dword v79, v124, s[14:15] nt
	s_add_u32 s14, s14, 0x2000
	s_addc_u32 s15, s15, 0
	global_load_dword v80, v124, s[14:15] nt
	s_add_u32 s14, s14, 0x2000
	s_addc_u32 s15, s15, 0
	global_load_dword v81, v124, s[14:15] nt
	s_add_u32 s14, s14, 0x2000
	s_addc_u32 s15, s15, 0
	global_load_dword v82, v124, s[14:15] nt
	s_add_u32 s14, s14, 0x2000
	s_addc_u32 s15, s15, 0
	global_load_dword v83, v124, s[14:15] nt
	s_add_u32 s14, s14, 0x2000
	s_addc_u32 s15, s15, 0
	global_load_dword v84, v124, s[14:15] nt
	s_add_u32 s14, s14, 0x2000
	s_addc_u32 s15, s15, 0
	global_load_dword v85, v124, s[14:15] nt
	s_add_u32 s14, s14, 0x2000
	s_addc_u32 s15, s15, 0
	global_load_dword v86, v124, s[14:15] nt
	s_add_u32 s14, s14, 0x2000
	s_addc_u32 s15, s15, 0
	global_load_dword v87, v124, s[14:15] nt
	s_add_u32 s14, s14, 0x2000
	s_addc_u32 s15, s15, 0
	global_load_dword v88, v124, s[14:15] nt
	s_add_u32 s14, s14, 0x2000
	s_addc_u32 s15, s15, 0
	global_load_dword v89, v124, s[14:15] nt
	s_add_u32 s14, s14, 0x2000
	s_addc_u32 s15, s15, 0
	global_load_dword v90, v124, s[14:15] nt
	s_add_u32 s14, s14, 0x2000
	s_addc_u32 s15, s15, 0
	global_load_dword v91, v124, s[14:15] nt
	s_add_u32 s14, s14, 0x2000
	s_addc_u32 s15, s15, 0
	global_load_dword v92, v124, s[14:15] nt
	s_add_u32 s14, s14, 0x2000
	s_addc_u32 s15, s15, 0
	global_load_dword v93, v124, s[14:15] nt
	s_add_u32 s14, s14, 0x2000
	s_addc_u32 s15, s15, 0
	global_load_dword v94, v124, s[14:15] nt
	s_add_u32 s14, s14, 0x2000
	s_addc_u32 s15, s15, 0
	global_load_dword v95, v124, s[14:15] nt
	s_add_u32 s14, s14, 0x2000
	s_addc_u32 s15, s15, 0
	global_load_dword v96, v124, s[14:15] nt
	s_add_u32 s14, s14, 0x2000
	s_addc_u32 s15, s15, 0
	global_load_dword v97, v124, s[14:15] nt
	s_add_u32 s14, s14, 0x2000
	s_addc_u32 s15, s15, 0
	global_load_dword v98, v124, s[14:15] nt
	s_add_u32 s14, s14, 0x2000
	s_addc_u32 s15, s15, 0
	global_load_dword v99, v124, s[14:15] nt
	s_add_u32 s14, s14, 0x2000
	s_addc_u32 s15, s15, 0
	global_load_dword v100, v124, s[14:15] nt
	s_add_u32 s14, s14, 0x2000
	s_addc_u32 s15, s15, 0
	global_load_dword v101, v124, s[14:15] nt
	s_add_u32 s14, s14, 0x2000
	s_addc_u32 s15, s15, 0
	global_load_dword v102, v124, s[14:15] nt
	s_add_u32 s14, s14, 0x2000
	s_addc_u32 s15, s15, 0
	global_load_dword v103, v124, s[14:15] nt
	s_add_u32 s14, s14, 0x2000
	s_addc_u32 s15, s15, 0
	global_load_dword v104, v124, s[14:15] nt
	s_add_u32 s14, s14, 0x2000
	s_addc_u32 s15, s15, 0
	global_load_dword v105, v124, s[14:15] nt
	s_add_u32 s14, s14, 0x2000
	s_addc_u32 s15, s15, 0
	global_load_dword v106, v124, s[14:15] nt
	s_add_u32 s14, s14, 0x2000
	s_addc_u32 s15, s15, 0
	global_load_dword v107, v124, s[14:15] nt
	s_add_u32 s14, s14, 0x2000
	s_addc_u32 s15, s15, 0
	global_load_dword v108, v124, s[14:15] nt
	s_add_u32 s14, s14, 0x2000
	s_addc_u32 s15, s15, 0
	global_load_dword v109, v124, s[14:15] nt
	s_add_u32 s14, s14, 0x2000
	s_addc_u32 s15, s15, 0
	global_load_dword v110, v124, s[14:15] nt
	s_add_u32 s14, s14, 0x2000
	s_addc_u32 s15, s15, 0
	global_load_dword v111, v124, s[14:15] nt
	s_add_u32 s14, s14, 0x2000
	s_addc_u32 s15, s15, 0
	global_load_dword v112, v124, s[14:15] nt
	s_add_u32 s14, s14, 0x2000
	s_addc_u32 s15, s15, 0
	global_load_dword v113, v124, s[14:15] nt
	s_add_u32 s14, s14, 0x2000
	s_addc_u32 s15, s15, 0
	global_load_dword v114, v124, s[14:15] nt
	s_add_u32 s14, s14, 0x2000
	s_addc_u32 s15, s15, 0
	global_load_dword v115, v124, s[14:15] nt
	s_add_u32 s14, s14, 0x2000
	s_addc_u32 s15, s15, 0
	global_load_dword v116, v124, s[14:15] nt
	s_add_u32 s14, s14, 0x2000
	s_addc_u32 s15, s15, 0
	global_load_dword v117, v124, s[14:15] nt
	s_add_u32 s14, s14, 0x2000
	s_addc_u32 s15, s15, 0
	global_load_dword v118, v124, s[14:15] nt
	s_add_u32 s14, s14, 0x2000
	s_addc_u32 s15, s15, 0
	global_load_dword v119, v124, s[14:15] nt
	s_add_u32 s14, s14, 0x2000
	s_addc_u32 s15, s15, 0
	global_load_dword v120, v124, s[14:15] nt
	s_add_u32 s14, s14, 0x2000
	s_addc_u32 s15, s15, 0
	global_load_dword v121, v124, s[14:15] nt
	s_add_u32 s14, s14, 0x2000
	s_addc_u32 s15, s15, 0
	global_load_dword v122, v124, s[14:15] nt
	s_add_u32 s14, s14, 0x2000
	s_addc_u32 s15, s15, 0
	global_load_dword v123, v124, s[14:15] nt
	s_waitcnt vmcnt(62)
	ds_write2_b32 v4, v60, v61 offset1:65
	s_waitcnt vmcnt(60)
	ds_write2_b32 v4, v62, v63 offset0:130 offset1:195
	v_add_u32_e32 v125, 0x400, v4
	s_waitcnt vmcnt(58)
	ds_write2_b32 v125, v64, v65 offset0:4 offset1:69
	s_waitcnt vmcnt(56)
	ds_write2_b32 v125, v66, v67 offset0:134 offset1:199
	v_add_u32_e32 v125, 0x800, v4
	s_waitcnt vmcnt(54)
	ds_write2_b32 v125, v68, v69 offset0:8 offset1:73
	s_waitcnt vmcnt(52)
	ds_write2_b32 v125, v70, v71 offset0:138 offset1:203
	v_add_u32_e32 v125, 0xc00, v4
	s_waitcnt vmcnt(50)
	ds_write2_b32 v125, v72, v73 offset0:12 offset1:77
	s_waitcnt vmcnt(48)
	ds_write2_b32 v125, v74, v75 offset0:142 offset1:207
	v_add_u32_e32 v125, 0x1040, v4
	s_waitcnt vmcnt(46)
	ds_write2_b32 v125, v76, v77 offset1:65
	s_waitcnt vmcnt(44)
	ds_write2_b32 v125, v78, v79 offset0:130 offset1:195
	v_add_u32_e32 v125, 0x1440, v4
	s_waitcnt vmcnt(42)
	ds_write2_b32 v125, v80, v81 offset0:4 offset1:69
	s_waitcnt vmcnt(40)
	ds_write2_b32 v125, v82, v83 offset0:134 offset1:199
	v_add_u32_e32 v125, 0x1840, v4
	s_waitcnt vmcnt(38)
	ds_write2_b32 v125, v84, v85 offset0:8 offset1:73
	s_waitcnt vmcnt(36)
	ds_write2_b32 v125, v86, v87 offset0:138 offset1:203
	v_add_u32_e32 v125, 0x1c40, v4
	s_waitcnt vmcnt(34)
	ds_write2_b32 v125, v88, v89 offset0:12 offset1:77
	s_waitcnt vmcnt(32)
	ds_write2_b32 v125, v90, v91 offset0:142 offset1:207
	v_add_u32_e32 v125, 0x2080, v4
	s_waitcnt vmcnt(30)
	ds_write2_b32 v125, v92, v93 offset1:65
	s_waitcnt vmcnt(28)
	ds_write2_b32 v125, v94, v95 offset0:130 offset1:195
	v_add_u32_e32 v125, 0x2480, v4
	s_waitcnt vmcnt(26)
	ds_write2_b32 v125, v96, v97 offset0:4 offset1:69
	s_waitcnt vmcnt(24)
	ds_write2_b32 v125, v98, v99 offset0:134 offset1:199
	v_add_u32_e32 v125, 0x2880, v4
	s_waitcnt vmcnt(22)
	ds_write2_b32 v125, v100, v101 offset0:8 offset1:73
	s_waitcnt vmcnt(20)
	ds_write2_b32 v125, v102, v103 offset0:138 offset1:203
	v_add_u32_e32 v125, 0x2c80, v4
	s_waitcnt vmcnt(18)
	ds_write2_b32 v125, v104, v105 offset0:12 offset1:77
	s_waitcnt vmcnt(16)
	ds_write2_b32 v125, v106, v107 offset0:142 offset1:207
	v_add_u32_e32 v125, 0x30c0, v4
	s_waitcnt vmcnt(14)
	ds_write2_b32 v125, v108, v109 offset1:65
	s_waitcnt vmcnt(12)
	ds_write2_b32 v125, v110, v111 offset0:130 offset1:195
	v_add_u32_e32 v125, 0x34c0, v4
	s_waitcnt vmcnt(10)
	ds_write2_b32 v125, v112, v113 offset0:4 offset1:69
	s_waitcnt vmcnt(8)
	ds_write2_b32 v125, v114, v115 offset0:134 offset1:199
	v_add_u32_e32 v125, 0x38c0, v4
	s_waitcnt vmcnt(6)
	ds_write2_b32 v125, v116, v117 offset0:8 offset1:73
	s_waitcnt vmcnt(4)
	ds_write2_b32 v125, v118, v119 offset0:138 offset1:203
	v_add_u32_e32 v125, 0x3cc0, v4
	s_waitcnt vmcnt(2)
	ds_write2_b32 v125, v120, v121 offset0:12 offset1:77
	s_waitcnt vmcnt(0)
	ds_write2_b32 v125, v122, v123 offset0:142 offset1:207
	v_add_u32_e32 v4, 0xffffc000, v1
	v_lshrrev_b32_e32 v25, 5, v4
	v_lshlrev_b32_e32 v27, 6, v4
	v_lshlrev_b32_e32 v29, 11, v25
	v_lshlrev_b32_e32 v4, 7, v25
	v_sub_u32_e32 v25, v27, v29
	s_waitcnt lgkmcnt(0)
	v_or_b32_e32 v60, v25, v39
	ds_read2_b32 v[34:35], v40 offset1:65
	v_ashrrev_i32_e32 v61, 31, v60
	s_waitcnt lgkmcnt(0)
	v_cvt_pk_bf16_f32 v34, v34, v35
	ds_read2_b32 v[36:37], v40 offset0:130 offset1:195
	v_add_u32_e32 v23, 0x400, v40
	v_lshl_add_u64 v[58:59], v[16:17], 0, v[4:5]
	v_lshlrev_b64 v[60:61], 13, v[60:61]
	s_waitcnt lgkmcnt(0)
	v_cvt_pk_bf16_f32 v35, v36, v37
	ds_read2_b32 v[36:37], v23 offset0:4 offset1:69
	v_lshl_add_u64 v[60:61], v[58:59], 0, v[60:61]
	s_waitcnt lgkmcnt(0)
	v_cvt_pk_bf16_f32 v36, v36, v37
	ds_read2_b32 v[56:57], v23 offset0:134 offset1:199
	s_waitcnt lgkmcnt(0)
	v_cvt_pk_bf16_f32 v37, v56, v57
	global_store_dwordx4 v[60:61], v[34:37], off
	v_or_b32_e32 v60, v25, v41
	v_ashrrev_i32_e32 v61, 31, v60
	ds_read2_b32 v[56:57], v40 offset0:8 offset1:73
	s_waitcnt lgkmcnt(0)
	v_cvt_pk_bf16_f32 v34, v56, v57
	ds_read2_b32 v[36:37], v40 offset0:138 offset1:203
	v_lshlrev_b64 v[60:61], 13, v[60:61]
	s_waitcnt lgkmcnt(0)
	v_cvt_pk_bf16_f32 v35, v36, v37
	ds_read2_b32 v[36:37], v23 offset0:12 offset1:77
	v_lshl_add_u64 v[60:61], v[58:59], 0, v[60:61]
	s_waitcnt lgkmcnt(0)
	v_cvt_pk_bf16_f32 v36, v36, v37
	ds_read2_b32 v[56:57], v23 offset0:142 offset1:207
	s_waitcnt lgkmcnt(0)
	v_cvt_pk_bf16_f32 v37, v56, v57
	global_store_dwordx4 v[60:61], v[34:37], off
	v_or_b32_e32 v60, v25, v42
	v_ashrrev_i32_e32 v61, 31, v60
	ds_read2_b32 v[56:57], v40 offset0:16 offset1:81
	s_waitcnt lgkmcnt(0)
	v_cvt_pk_bf16_f32 v34, v56, v57
	ds_read2_b32 v[36:37], v40 offset0:146 offset1:211
	v_lshlrev_b64 v[60:61], 13, v[60:61]
	s_waitcnt lgkmcnt(0)
	v_cvt_pk_bf16_f32 v35, v36, v37
	ds_read2_b32 v[36:37], v23 offset0:20 offset1:85
	v_lshl_add_u64 v[60:61], v[58:59], 0, v[60:61]
	s_waitcnt lgkmcnt(0)
	v_cvt_pk_bf16_f32 v36, v36, v37
	ds_read2_b32 v[56:57], v23 offset0:150 offset1:215
	s_waitcnt lgkmcnt(0)
	v_cvt_pk_bf16_f32 v37, v56, v57
	global_store_dwordx4 v[60:61], v[34:37], off
	v_or_b32_e32 v60, v25, v43
	v_ashrrev_i32_e32 v61, 31, v60
	ds_read2_b32 v[56:57], v40 offset0:24 offset1:89
	s_waitcnt lgkmcnt(0)
	v_cvt_pk_bf16_f32 v34, v56, v57
	ds_read2_b32 v[36:37], v40 offset0:154 offset1:219
	v_lshlrev_b64 v[60:61], 13, v[60:61]
	s_waitcnt lgkmcnt(0)
	v_cvt_pk_bf16_f32 v35, v36, v37
	ds_read2_b32 v[36:37], v23 offset0:28 offset1:93
	v_lshl_add_u64 v[60:61], v[58:59], 0, v[60:61]
	s_waitcnt lgkmcnt(0)
	v_cvt_pk_bf16_f32 v36, v36, v37
	ds_read2_b32 v[56:57], v23 offset0:158 offset1:223
	s_waitcnt lgkmcnt(0)
	v_cvt_pk_bf16_f32 v37, v56, v57
	global_store_dwordx4 v[60:61], v[34:37], off
	v_or_b32_e32 v60, v25, v44
	v_ashrrev_i32_e32 v61, 31, v60
	ds_read2_b32 v[56:57], v40 offset0:32 offset1:97
	s_waitcnt lgkmcnt(0)
	v_cvt_pk_bf16_f32 v34, v56, v57
	ds_read2_b32 v[36:37], v40 offset0:162 offset1:227
	v_lshlrev_b64 v[60:61], 13, v[60:61]
	s_waitcnt lgkmcnt(0)
	v_cvt_pk_bf16_f32 v35, v36, v37
	ds_read2_b32 v[36:37], v23 offset0:36 offset1:101
	v_lshl_add_u64 v[60:61], v[58:59], 0, v[60:61]
	s_waitcnt lgkmcnt(0)
	v_cvt_pk_bf16_f32 v36, v36, v37
	ds_read2_b32 v[56:57], v23 offset0:166 offset1:231
	s_waitcnt lgkmcnt(0)
	v_cvt_pk_bf16_f32 v37, v56, v57
	global_store_dwordx4 v[60:61], v[34:37], off
	v_or_b32_e32 v60, v25, v45
	v_ashrrev_i32_e32 v61, 31, v60
	ds_read2_b32 v[56:57], v40 offset0:40 offset1:105
	s_waitcnt lgkmcnt(0)
	v_cvt_pk_bf16_f32 v34, v56, v57
	ds_read2_b32 v[36:37], v40 offset0:170 offset1:235
	v_lshlrev_b64 v[60:61], 13, v[60:61]
	s_waitcnt lgkmcnt(0)
	v_cvt_pk_bf16_f32 v35, v36, v37
	ds_read2_b32 v[36:37], v23 offset0:44 offset1:109
	v_lshl_add_u64 v[60:61], v[58:59], 0, v[60:61]
	s_waitcnt lgkmcnt(0)
	v_cvt_pk_bf16_f32 v36, v36, v37
	ds_read2_b32 v[56:57], v23 offset0:174 offset1:239
	s_waitcnt lgkmcnt(0)
	v_cvt_pk_bf16_f32 v37, v56, v57
	global_store_dwordx4 v[60:61], v[34:37], off
	v_or_b32_e32 v60, v25, v46
	ds_read2_b32 v[56:57], v40 offset0:48 offset1:113
	s_waitcnt lgkmcnt(0)
	v_cvt_pk_bf16_f32 v34, v56, v57
	ds_read2_b32 v[36:37], v40 offset0:178 offset1:243
	v_ashrrev_i32_e32 v61, 31, v60
	s_waitcnt lgkmcnt(0)
	v_cvt_pk_bf16_f32 v35, v36, v37
	ds_read2_b32 v[36:37], v23 offset0:52 offset1:117
	v_lshlrev_b64 v[60:61], 13, v[60:61]
	s_waitcnt lgkmcnt(0)
	v_cvt_pk_bf16_f32 v36, v36, v37
	ds_read2_b32 v[56:57], v23 offset0:182 offset1:247
	s_waitcnt lgkmcnt(0)
	v_cvt_pk_bf16_f32 v37, v56, v57
	v_lshl_add_u64 v[60:61], v[58:59], 0, v[60:61]
	ds_read2_b32 v[56:57], v40 offset0:56 offset1:121
	global_store_dwordx4 v[60:61], v[34:37], off
	v_or_b32_e32 v60, v25, v47
	v_ashrrev_i32_e32 v61, 31, v60
	s_waitcnt lgkmcnt(0)
	v_cvt_pk_bf16_f32 v34, v56, v57
	ds_read2_b32 v[36:37], v40 offset0:186 offset1:251
	s_waitcnt lgkmcnt(0)
	v_cvt_pk_bf16_f32 v35, v36, v37
	ds_read2_b32 v[36:37], v23 offset0:60 offset1:125
	s_waitcnt lgkmcnt(0)
	v_cvt_pk_bf16_f32 v36, v36, v37
	ds_read2_b32 v[56:57], v23 offset0:190 offset1:255
	v_lshlrev_b64 v[60:61], 13, v[60:61]
	s_waitcnt lgkmcnt(0)
	v_cvt_pk_bf16_f32 v37, v56, v57
	v_lshl_add_u64 v[56:57], v[58:59], 0, v[60:61]
	global_store_dwordx4 v[56:57], v[34:37], off
	s_waitcnt lgkmcnt(0)

.LBB0_58:
	v_readfirstlane_b32 s12, v34
	v_readfirstlane_b32 s13, v35
	s_nop 4
	v_subrev_u32_e32 v124, s12, v34
	global_load_dword v60, v124, s[12:13] nt
	s_add_u32 s12, s12, 0x10000
	s_addc_u32 s13, s13, 0
	global_load_dword v61, v124, s[12:13] nt
	s_add_u32 s12, s12, 0x10000
	s_addc_u32 s13, s13, 0
	global_load_dword v62, v124, s[12:13] nt
	s_add_u32 s12, s12, 0x10000
	s_addc_u32 s13, s13, 0
	global_load_dword v63, v124, s[12:13] nt
	s_add_u32 s12, s12, 0x10000
	s_addc_u32 s13, s13, 0
	global_load_dword v64, v124, s[12:13] nt
	s_add_u32 s12, s12, 0x10000
	s_addc_u32 s13, s13, 0
	global_load_dword v65, v124, s[12:13] nt
	s_add_u32 s12, s12, 0x10000
	s_addc_u32 s13, s13, 0
	global_load_dword v66, v124, s[12:13] nt
	s_add_u32 s12, s12, 0x10000
	s_addc_u32 s13, s13, 0
	global_load_dword v67, v124, s[12:13] nt
	s_add_u32 s12, s12, 0x10000
	s_addc_u32 s13, s13, 0
	global_load_dword v68, v124, s[12:13] nt
	s_add_u32 s12, s12, 0x10000
	s_addc_u32 s13, s13, 0
	global_load_dword v69, v124, s[12:13] nt
	s_add_u32 s12, s12, 0x10000
	s_addc_u32 s13, s13, 0
	global_load_dword v70, v124, s[12:13] nt
	s_add_u32 s12, s12, 0x10000
	s_addc_u32 s13, s13, 0
	global_load_dword v71, v124, s[12:13] nt
	s_add_u32 s12, s12, 0x10000
	s_addc_u32 s13, s13, 0
	global_load_dword v72, v124, s[12:13] nt
	s_add_u32 s12, s12, 0x10000
	s_addc_u32 s13, s13, 0
	global_load_dword v73, v124, s[12:13] nt
	s_add_u32 s12, s12, 0x10000
	s_addc_u32 s13, s13, 0
	global_load_dword v74, v124, s[12:13] nt
	s_add_u32 s12, s12, 0x10000
	s_addc_u32 s13, s13, 0
	global_load_dword v75, v124, s[12:13] nt
	s_add_u32 s12, s12, 0x10000
	s_addc_u32 s13, s13, 0
	global_load_dword v76, v124, s[12:13] nt
	s_add_u32 s12, s12, 0x10000
	s_addc_u32 s13, s13, 0
	global_load_dword v77, v124, s[12:13] nt
	s_add_u32 s12, s12, 0x10000
	s_addc_u32 s13, s13, 0
	global_load_dword v78, v124, s[12:13] nt
	s_add_u32 s12, s12, 0x10000
	s_addc_u32 s13, s13, 0
	global_load_dword v79, v124, s[12:13] nt
	s_add_u32 s12, s12, 0x10000
	s_addc_u32 s13, s13, 0
	global_load_dword v80, v124, s[12:13] nt
	s_add_u32 s12, s12, 0x10000
	s_addc_u32 s13, s13, 0
	global_load_dword v81, v124, s[12:13] nt
	s_add_u32 s12, s12, 0x10000
	s_addc_u32 s13, s13, 0
	global_load_dword v82, v124, s[12:13] nt
	s_add_u32 s12, s12, 0x10000
	s_addc_u32 s13, s13, 0
	global_load_dword v83, v124, s[12:13] nt
	s_add_u32 s12, s12, 0x10000
	s_addc_u32 s13, s13, 0
	global_load_dword v84, v124, s[12:13] nt
	s_add_u32 s12, s12, 0x10000
	s_addc_u32 s13, s13, 0
	global_load_dword v85, v124, s[12:13] nt
	s_add_u32 s12, s12, 0x10000
	s_addc_u32 s13, s13, 0
	global_load_dword v86, v124, s[12:13] nt
	s_add_u32 s12, s12, 0x10000
	s_addc_u32 s13, s13, 0
	global_load_dword v87, v124, s[12:13] nt
	s_add_u32 s12, s12, 0x10000
	s_addc_u32 s13, s13, 0
	global_load_dword v88, v124, s[12:13] nt
	s_add_u32 s12, s12, 0x10000
	s_addc_u32 s13, s13, 0
	global_load_dword v89, v124, s[12:13] nt
	s_add_u32 s12, s12, 0x10000
	s_addc_u32 s13, s13, 0
	global_load_dword v90, v124, s[12:13] nt
	s_add_u32 s12, s12, 0x10000
	s_addc_u32 s13, s13, 0
	global_load_dword v91, v124, s[12:13] nt
	s_add_u32 s12, s12, 0x10000
	s_addc_u32 s13, s13, 0
	global_load_dword v92, v124, s[12:13] nt
	s_add_u32 s12, s12, 0x10000
	s_addc_u32 s13, s13, 0
	global_load_dword v93, v124, s[12:13] nt
	s_add_u32 s12, s12, 0x10000
	s_addc_u32 s13, s13, 0
	global_load_dword v94, v124, s[12:13] nt
	s_add_u32 s12, s12, 0x10000
	s_addc_u32 s13, s13, 0
	global_load_dword v95, v124, s[12:13] nt
	s_add_u32 s12, s12, 0x10000
	s_addc_u32 s13, s13, 0
	global_load_dword v96, v124, s[12:13] nt
	s_add_u32 s12, s12, 0x10000
	s_addc_u32 s13, s13, 0
	global_load_dword v97, v124, s[12:13] nt
	s_add_u32 s12, s12, 0x10000
	s_addc_u32 s13, s13, 0
	global_load_dword v98, v124, s[12:13] nt
	s_add_u32 s12, s12, 0x10000
	s_addc_u32 s13, s13, 0
	global_load_dword v99, v124, s[12:13] nt
	s_add_u32 s12, s12, 0x10000
	s_addc_u32 s13, s13, 0
	global_load_dword v100, v124, s[12:13] nt
	s_add_u32 s12, s12, 0x10000
	s_addc_u32 s13, s13, 0
	global_load_dword v101, v124, s[12:13] nt
	s_add_u32 s12, s12, 0x10000
	s_addc_u32 s13, s13, 0
	global_load_dword v102, v124, s[12:13] nt
	s_add_u32 s12, s12, 0x10000
	s_addc_u32 s13, s13, 0
	global_load_dword v103, v124, s[12:13] nt
	s_add_u32 s12, s12, 0x10000
	s_addc_u32 s13, s13, 0
	global_load_dword v104, v124, s[12:13] nt
	s_add_u32 s12, s12, 0x10000
	s_addc_u32 s13, s13, 0
	global_load_dword v105, v124, s[12:13] nt
	s_add_u32 s12, s12, 0x10000
	s_addc_u32 s13, s13, 0
	global_load_dword v106, v124, s[12:13] nt
	s_add_u32 s12, s12, 0x10000
	s_addc_u32 s13, s13, 0
	global_load_dword v107, v124, s[12:13] nt
	s_add_u32 s12, s12, 0x10000
	s_addc_u32 s13, s13, 0
	global_load_dword v108, v124, s[12:13] nt
	s_add_u32 s12, s12, 0x10000
	s_addc_u32 s13, s13, 0
	global_load_dword v109, v124, s[12:13] nt
	s_add_u32 s12, s12, 0x10000
	s_addc_u32 s13, s13, 0
	global_load_dword v110, v124, s[12:13] nt
	s_add_u32 s12, s12, 0x10000
	s_addc_u32 s13, s13, 0
	global_load_dword v111, v124, s[12:13] nt
	s_add_u32 s12, s12, 0x10000
	s_addc_u32 s13, s13, 0
	global_load_dword v112, v124, s[12:13] nt
	s_add_u32 s12, s12, 0x10000
	s_addc_u32 s13, s13, 0
	global_load_dword v113, v124, s[12:13] nt
	s_add_u32 s12, s12, 0x10000
	s_addc_u32 s13, s13, 0
	global_load_dword v114, v124, s[12:13] nt
	s_add_u32 s12, s12, 0x10000
	s_addc_u32 s13, s13, 0
	global_load_dword v115, v124, s[12:13] nt
	s_add_u32 s12, s12, 0x10000
	s_addc_u32 s13, s13, 0
	global_load_dword v116, v124, s[12:13] nt
	s_add_u32 s12, s12, 0x10000
	s_addc_u32 s13, s13, 0
	global_load_dword v117, v124, s[12:13] nt
	s_add_u32 s12, s12, 0x10000
	s_addc_u32 s13, s13, 0
	global_load_dword v118, v124, s[12:13] nt
	s_add_u32 s12, s12, 0x10000
	s_addc_u32 s13, s13, 0
	global_load_dword v119, v124, s[12:13] nt
	s_add_u32 s12, s12, 0x10000
	s_addc_u32 s13, s13, 0
	global_load_dword v120, v124, s[12:13] nt
	s_add_u32 s12, s12, 0x10000
	s_addc_u32 s13, s13, 0
	global_load_dword v121, v124, s[12:13] nt
	s_add_u32 s12, s12, 0x10000
	s_addc_u32 s13, s13, 0
	global_load_dword v122, v124, s[12:13] nt
	s_add_u32 s12, s12, 0x10000
	s_addc_u32 s13, s13, 0
	global_load_dword v123, v124, s[12:13] nt
	s_waitcnt vmcnt(62)
	ds_write2_b32 v4, v60, v61 offset1:65
	s_waitcnt vmcnt(60)
	ds_write2_b32 v4, v62, v63 offset0:130 offset1:195
	v_add_u32_e32 v125, 0x400, v4
	s_waitcnt vmcnt(58)
	ds_write2_b32 v125, v64, v65 offset0:4 offset1:69
	s_waitcnt vmcnt(56)
	ds_write2_b32 v125, v66, v67 offset0:134 offset1:199
	v_add_u32_e32 v125, 0x800, v4
	s_waitcnt vmcnt(54)
	ds_write2_b32 v125, v68, v69 offset0:8 offset1:73
	s_waitcnt vmcnt(52)
	ds_write2_b32 v125, v70, v71 offset0:138 offset1:203
	v_add_u32_e32 v125, 0xc00, v4
	s_waitcnt vmcnt(50)
	ds_write2_b32 v125, v72, v73 offset0:12 offset1:77
	s_waitcnt vmcnt(48)
	ds_write2_b32 v125, v74, v75 offset0:142 offset1:207
	v_add_u32_e32 v125, 0x1040, v4
	s_waitcnt vmcnt(46)
	ds_write2_b32 v125, v76, v77 offset1:65
	s_waitcnt vmcnt(44)
	ds_write2_b32 v125, v78, v79 offset0:130 offset1:195
	v_add_u32_e32 v125, 0x1440, v4
	s_waitcnt vmcnt(42)
	ds_write2_b32 v125, v80, v81 offset0:4 offset1:69
	s_waitcnt vmcnt(40)
	ds_write2_b32 v125, v82, v83 offset0:134 offset1:199
	v_add_u32_e32 v125, 0x1840, v4
	s_waitcnt vmcnt(38)
	ds_write2_b32 v125, v84, v85 offset0:8 offset1:73
	s_waitcnt vmcnt(36)
	ds_write2_b32 v125, v86, v87 offset0:138 offset1:203
	v_add_u32_e32 v125, 0x1c40, v4
	s_waitcnt vmcnt(34)
	ds_write2_b32 v125, v88, v89 offset0:12 offset1:77
	s_waitcnt vmcnt(32)
	ds_write2_b32 v125, v90, v91 offset0:142 offset1:207
	v_add_u32_e32 v125, 0x2080, v4
	s_waitcnt vmcnt(30)
	ds_write2_b32 v125, v92, v93 offset1:65
	s_waitcnt vmcnt(28)
	ds_write2_b32 v125, v94, v95 offset0:130 offset1:195
	v_add_u32_e32 v125, 0x2480, v4
	s_waitcnt vmcnt(26)
	ds_write2_b32 v125, v96, v97 offset0:4 offset1:69
	s_waitcnt vmcnt(24)
	ds_write2_b32 v125, v98, v99 offset0:134 offset1:199
	v_add_u32_e32 v125, 0x2880, v4
	s_waitcnt vmcnt(22)
	ds_write2_b32 v125, v100, v101 offset0:8 offset1:73
	s_waitcnt vmcnt(20)
	ds_write2_b32 v125, v102, v103 offset0:138 offset1:203
	v_add_u32_e32 v125, 0x2c80, v4
	s_waitcnt vmcnt(18)
	ds_write2_b32 v125, v104, v105 offset0:12 offset1:77
	s_waitcnt vmcnt(16)
	ds_write2_b32 v125, v106, v107 offset0:142 offset1:207
	v_add_u32_e32 v125, 0x30c0, v4
	s_waitcnt vmcnt(14)
	ds_write2_b32 v125, v108, v109 offset1:65
	s_waitcnt vmcnt(12)
	ds_write2_b32 v125, v110, v111 offset0:130 offset1:195
	v_add_u32_e32 v125, 0x34c0, v4
	s_waitcnt vmcnt(10)
	ds_write2_b32 v125, v112, v113 offset0:4 offset1:69
	s_waitcnt vmcnt(8)
	ds_write2_b32 v125, v114, v115 offset0:134 offset1:199
	v_add_u32_e32 v125, 0x38c0, v4
	s_waitcnt vmcnt(6)
	ds_write2_b32 v125, v116, v117 offset0:8 offset1:73
	s_waitcnt vmcnt(4)
	ds_write2_b32 v125, v118, v119 offset0:138 offset1:203
	v_add_u32_e32 v125, 0x3cc0, v4
	s_waitcnt vmcnt(2)
	ds_write2_b32 v125, v120, v121 offset0:12 offset1:77
	s_waitcnt vmcnt(0)
	ds_write2_b32 v125, v122, v123 offset0:142 offset1:207
	v_add_u32_e32 v4, 0xffffe000, v1
	v_lshrrev_b32_e32 v25, 8, v4
	v_lshlrev_b32_e32 v27, 6, v4
	v_lshlrev_b32_e32 v29, 14, v25
	v_lshlrev_b32_e32 v4, 7, v25
	v_sub_u32_e32 v25, v27, v29
	s_waitcnt lgkmcnt(0)
	v_or_b32_e32 v60, v25, v39
	ds_read2_b32 v[34:35], v40 offset1:65
	v_ashrrev_i32_e32 v61, 31, v60
	s_waitcnt lgkmcnt(0)
	v_cvt_pk_bf16_f32 v34, v34, v35
	ds_read2_b32 v[36:37], v40 offset0:130 offset1:195
	v_add_u32_e32 v23, 0x400, v40
	v_lshl_add_u64 v[58:59], v[18:19], 0, v[4:5]
	v_lshlrev_b64 v[60:61], 12, v[60:61]
	s_waitcnt lgkmcnt(0)
	v_cvt_pk_bf16_f32 v35, v36, v37
	ds_read2_b32 v[36:37], v23 offset0:4 offset1:69
	v_lshl_add_u64 v[60:61], v[58:59], 0, v[60:61]
	s_waitcnt lgkmcnt(0)
	v_cvt_pk_bf16_f32 v36, v36, v37
	ds_read2_b32 v[56:57], v23 offset0:134 offset1:199
	s_waitcnt lgkmcnt(0)
	v_cvt_pk_bf16_f32 v37, v56, v57
	global_store_dwordx4 v[60:61], v[34:37], off
	v_or_b32_e32 v60, v25, v41
	v_ashrrev_i32_e32 v61, 31, v60
	ds_read2_b32 v[56:57], v40 offset0:8 offset1:73
	s_waitcnt lgkmcnt(0)
	v_cvt_pk_bf16_f32 v34, v56, v57
	ds_read2_b32 v[36:37], v40 offset0:138 offset1:203
	v_lshlrev_b64 v[60:61], 12, v[60:61]
	s_waitcnt lgkmcnt(0)
	v_cvt_pk_bf16_f32 v35, v36, v37
	ds_read2_b32 v[36:37], v23 offset0:12 offset1:77
	v_lshl_add_u64 v[60:61], v[58:59], 0, v[60:61]
	s_waitcnt lgkmcnt(0)
	v_cvt_pk_bf16_f32 v36, v36, v37
	ds_read2_b32 v[56:57], v23 offset0:142 offset1:207
	s_waitcnt lgkmcnt(0)
	v_cvt_pk_bf16_f32 v37, v56, v57
	global_store_dwordx4 v[60:61], v[34:37], off
	v_or_b32_e32 v60, v25, v42
	v_ashrrev_i32_e32 v61, 31, v60
	ds_read2_b32 v[56:57], v40 offset0:16 offset1:81
	s_waitcnt lgkmcnt(0)
	v_cvt_pk_bf16_f32 v34, v56, v57
	ds_read2_b32 v[36:37], v40 offset0:146 offset1:211
	v_lshlrev_b64 v[60:61], 12, v[60:61]
	s_waitcnt lgkmcnt(0)
	v_cvt_pk_bf16_f32 v35, v36, v37
	ds_read2_b32 v[36:37], v23 offset0:20 offset1:85
	v_lshl_add_u64 v[60:61], v[58:59], 0, v[60:61]
	s_waitcnt lgkmcnt(0)
	v_cvt_pk_bf16_f32 v36, v36, v37
	ds_read2_b32 v[56:57], v23 offset0:150 offset1:215
	s_waitcnt lgkmcnt(0)
	v_cvt_pk_bf16_f32 v37, v56, v57
	global_store_dwordx4 v[60:61], v[34:37], off
	v_or_b32_e32 v60, v25, v43
	v_ashrrev_i32_e32 v61, 31, v60
	ds_read2_b32 v[56:57], v40 offset0:24 offset1:89
	s_waitcnt lgkmcnt(0)
	v_cvt_pk_bf16_f32 v34, v56, v57
	ds_read2_b32 v[36:37], v40 offset0:154 offset1:219
	v_lshlrev_b64 v[60:61], 12, v[60:61]
	s_waitcnt lgkmcnt(0)
	v_cvt_pk_bf16_f32 v35, v36, v37
	ds_read2_b32 v[36:37], v23 offset0:28 offset1:93
	v_lshl_add_u64 v[60:61], v[58:59], 0, v[60:61]
	s_waitcnt lgkmcnt(0)
	v_cvt_pk_bf16_f32 v36, v36, v37
	ds_read2_b32 v[56:57], v23 offset0:158 offset1:223
	s_waitcnt lgkmcnt(0)
	v_cvt_pk_bf16_f32 v37, v56, v57
	global_store_dwordx4 v[60:61], v[34:37], off
	v_or_b32_e32 v60, v25, v44
	v_ashrrev_i32_e32 v61, 31, v60
	ds_read2_b32 v[56:57], v40 offset0:32 offset1:97
	s_waitcnt lgkmcnt(0)
	v_cvt_pk_bf16_f32 v34, v56, v57
	ds_read2_b32 v[36:37], v40 offset0:162 offset1:227
	v_lshlrev_b64 v[60:61], 12, v[60:61]
	s_waitcnt lgkmcnt(0)
	v_cvt_pk_bf16_f32 v35, v36, v37
	ds_read2_b32 v[36:37], v23 offset0:36 offset1:101
	v_lshl_add_u64 v[60:61], v[58:59], 0, v[60:61]
	s_waitcnt lgkmcnt(0)
	v_cvt_pk_bf16_f32 v36, v36, v37
	ds_read2_b32 v[56:57], v23 offset0:166 offset1:231
	s_waitcnt lgkmcnt(0)
	v_cvt_pk_bf16_f32 v37, v56, v57
	global_store_dwordx4 v[60:61], v[34:37], off
	v_or_b32_e32 v60, v25, v45
	v_ashrrev_i32_e32 v61, 31, v60
	ds_read2_b32 v[56:57], v40 offset0:40 offset1:105
	s_waitcnt lgkmcnt(0)
	v_cvt_pk_bf16_f32 v34, v56, v57
	ds_read2_b32 v[36:37], v40 offset0:170 offset1:235
	v_lshlrev_b64 v[60:61], 12, v[60:61]
	s_waitcnt lgkmcnt(0)
	v_cvt_pk_bf16_f32 v35, v36, v37
	ds_read2_b32 v[36:37], v23 offset0:44 offset1:109
	v_lshl_add_u64 v[60:61], v[58:59], 0, v[60:61]
	s_waitcnt lgkmcnt(0)
	v_cvt_pk_bf16_f32 v36, v36, v37
	ds_read2_b32 v[56:57], v23 offset0:174 offset1:239
	s_waitcnt lgkmcnt(0)
	v_cvt_pk_bf16_f32 v37, v56, v57
	global_store_dwordx4 v[60:61], v[34:37], off
	v_or_b32_e32 v60, v25, v46
	ds_read2_b32 v[56:57], v40 offset0:48 offset1:113
	s_waitcnt lgkmcnt(0)
	v_cvt_pk_bf16_f32 v34, v56, v57
	ds_read2_b32 v[36:37], v40 offset0:178 offset1:243
	v_ashrrev_i32_e32 v61, 31, v60
	s_waitcnt lgkmcnt(0)
	v_cvt_pk_bf16_f32 v35, v36, v37
	ds_read2_b32 v[36:37], v23 offset0:52 offset1:117
	v_lshlrev_b64 v[60:61], 12, v[60:61]
	s_waitcnt lgkmcnt(0)
	v_cvt_pk_bf16_f32 v36, v36, v37
	ds_read2_b32 v[56:57], v23 offset0:182 offset1:247
	s_waitcnt lgkmcnt(0)
	v_cvt_pk_bf16_f32 v37, v56, v57
	v_lshl_add_u64 v[60:61], v[58:59], 0, v[60:61]
	ds_read2_b32 v[56:57], v40 offset0:56 offset1:121
	global_store_dwordx4 v[60:61], v[34:37], off
	v_or_b32_e32 v60, v25, v47
	v_ashrrev_i32_e32 v61, 31, v60
	s_waitcnt lgkmcnt(0)
	v_cvt_pk_bf16_f32 v34, v56, v57
	ds_read2_b32 v[36:37], v40 offset0:186 offset1:251
	s_waitcnt lgkmcnt(0)
	v_cvt_pk_bf16_f32 v35, v36, v37
	ds_read2_b32 v[36:37], v23 offset0:60 offset1:125
	s_waitcnt lgkmcnt(0)
	v_cvt_pk_bf16_f32 v36, v36, v37
	ds_read2_b32 v[56:57], v23 offset0:190 offset1:255
	v_lshlrev_b64 v[60:61], 12, v[60:61]
	s_waitcnt lgkmcnt(0)
	v_cvt_pk_bf16_f32 v37, v56, v57
	v_lshl_add_u64 v[56:57], v[58:59], 0, v[60:61]
	global_store_dwordx4 v[56:57], v[34:37], off
	s_waitcnt lgkmcnt(0)

.LBB0_63:
	v_readfirstlane_b32 s10, v34
	v_readfirstlane_b32 s11, v35
	s_nop 4
	v_subrev_u32_e32 v124, s10, v34
	global_load_dword v60, v124, s[10:11] nt
	s_add_u32 s10, s10, 0x2000
	s_addc_u32 s11, s11, 0
	global_load_dword v61, v124, s[10:11] nt
	s_add_u32 s10, s10, 0x2000
	s_addc_u32 s11, s11, 0
	global_load_dword v62, v124, s[10:11] nt
	s_add_u32 s10, s10, 0x2000
	s_addc_u32 s11, s11, 0
	global_load_dword v63, v124, s[10:11] nt
	s_add_u32 s10, s10, 0x2000
	s_addc_u32 s11, s11, 0
	global_load_dword v64, v124, s[10:11] nt
	s_add_u32 s10, s10, 0x2000
	s_addc_u32 s11, s11, 0
	global_load_dword v65, v124, s[10:11] nt
	s_add_u32 s10, s10, 0x2000
	s_addc_u32 s11, s11, 0
	global_load_dword v66, v124, s[10:11] nt
	s_add_u32 s10, s10, 0x2000
	s_addc_u32 s11, s11, 0
	global_load_dword v67, v124, s[10:11] nt
	s_add_u32 s10, s10, 0x2000
	s_addc_u32 s11, s11, 0
	global_load_dword v68, v124, s[10:11] nt
	s_add_u32 s10, s10, 0x2000
	s_addc_u32 s11, s11, 0
	global_load_dword v69, v124, s[10:11] nt
	s_add_u32 s10, s10, 0x2000
	s_addc_u32 s11, s11, 0
	global_load_dword v70, v124, s[10:11] nt
	s_add_u32 s10, s10, 0x2000
	s_addc_u32 s11, s11, 0
	global_load_dword v71, v124, s[10:11] nt
	s_add_u32 s10, s10, 0x2000
	s_addc_u32 s11, s11, 0
	global_load_dword v72, v124, s[10:11] nt
	s_add_u32 s10, s10, 0x2000
	s_addc_u32 s11, s11, 0
	global_load_dword v73, v124, s[10:11] nt
	s_add_u32 s10, s10, 0x2000
	s_addc_u32 s11, s11, 0
	global_load_dword v74, v124, s[10:11] nt
	s_add_u32 s10, s10, 0x2000
	s_addc_u32 s11, s11, 0
	global_load_dword v75, v124, s[10:11] nt
	s_add_u32 s10, s10, 0x2000
	s_addc_u32 s11, s11, 0
	global_load_dword v76, v124, s[10:11] nt
	s_add_u32 s10, s10, 0x2000
	s_addc_u32 s11, s11, 0
	global_load_dword v77, v124, s[10:11] nt
	s_add_u32 s10, s10, 0x2000
	s_addc_u32 s11, s11, 0
	global_load_dword v78, v124, s[10:11] nt
	s_add_u32 s10, s10, 0x2000
	s_addc_u32 s11, s11, 0
	global_load_dword v79, v124, s[10:11] nt
	s_add_u32 s10, s10, 0x2000
	s_addc_u32 s11, s11, 0
	global_load_dword v80, v124, s[10:11] nt
	s_add_u32 s10, s10, 0x2000
	s_addc_u32 s11, s11, 0
	global_load_dword v81, v124, s[10:11] nt
	s_add_u32 s10, s10, 0x2000
	s_addc_u32 s11, s11, 0
	global_load_dword v82, v124, s[10:11] nt
	s_add_u32 s10, s10, 0x2000
	s_addc_u32 s11, s11, 0
	global_load_dword v83, v124, s[10:11] nt
	s_add_u32 s10, s10, 0x2000
	s_addc_u32 s11, s11, 0
	global_load_dword v84, v124, s[10:11] nt
	s_add_u32 s10, s10, 0x2000
	s_addc_u32 s11, s11, 0
	global_load_dword v85, v124, s[10:11] nt
	s_add_u32 s10, s10, 0x2000
	s_addc_u32 s11, s11, 0
	global_load_dword v86, v124, s[10:11] nt
	s_add_u32 s10, s10, 0x2000
	s_addc_u32 s11, s11, 0
	global_load_dword v87, v124, s[10:11] nt
	s_add_u32 s10, s10, 0x2000
	s_addc_u32 s11, s11, 0
	global_load_dword v88, v124, s[10:11] nt
	s_add_u32 s10, s10, 0x2000
	s_addc_u32 s11, s11, 0
	global_load_dword v89, v124, s[10:11] nt
	s_add_u32 s10, s10, 0x2000
	s_addc_u32 s11, s11, 0
	global_load_dword v90, v124, s[10:11] nt
	s_add_u32 s10, s10, 0x2000
	s_addc_u32 s11, s11, 0
	global_load_dword v91, v124, s[10:11] nt
	s_add_u32 s10, s10, 0x2000
	s_addc_u32 s11, s11, 0
	global_load_dword v92, v124, s[10:11] nt
	s_add_u32 s10, s10, 0x2000
	s_addc_u32 s11, s11, 0
	global_load_dword v93, v124, s[10:11] nt
	s_add_u32 s10, s10, 0x2000
	s_addc_u32 s11, s11, 0
	global_load_dword v94, v124, s[10:11] nt
	s_add_u32 s10, s10, 0x2000
	s_addc_u32 s11, s11, 0
	global_load_dword v95, v124, s[10:11] nt
	s_add_u32 s10, s10, 0x2000
	s_addc_u32 s11, s11, 0
	global_load_dword v96, v124, s[10:11] nt
	s_add_u32 s10, s10, 0x2000
	s_addc_u32 s11, s11, 0
	global_load_dword v97, v124, s[10:11] nt
	s_add_u32 s10, s10, 0x2000
	s_addc_u32 s11, s11, 0
	global_load_dword v98, v124, s[10:11] nt
	s_add_u32 s10, s10, 0x2000
	s_addc_u32 s11, s11, 0
	global_load_dword v99, v124, s[10:11] nt
	s_add_u32 s10, s10, 0x2000
	s_addc_u32 s11, s11, 0
	global_load_dword v100, v124, s[10:11] nt
	s_add_u32 s10, s10, 0x2000
	s_addc_u32 s11, s11, 0
	global_load_dword v101, v124, s[10:11] nt
	s_add_u32 s10, s10, 0x2000
	s_addc_u32 s11, s11, 0
	global_load_dword v102, v124, s[10:11] nt
	s_add_u32 s10, s10, 0x2000
	s_addc_u32 s11, s11, 0
	global_load_dword v103, v124, s[10:11] nt
	s_add_u32 s10, s10, 0x2000
	s_addc_u32 s11, s11, 0
	global_load_dword v104, v124, s[10:11] nt
	s_add_u32 s10, s10, 0x2000
	s_addc_u32 s11, s11, 0
	global_load_dword v105, v124, s[10:11] nt
	s_add_u32 s10, s10, 0x2000
	s_addc_u32 s11, s11, 0
	global_load_dword v106, v124, s[10:11] nt
	s_add_u32 s10, s10, 0x2000
	s_addc_u32 s11, s11, 0
	global_load_dword v107, v124, s[10:11] nt
	s_add_u32 s10, s10, 0x2000
	s_addc_u32 s11, s11, 0
	global_load_dword v108, v124, s[10:11] nt
	s_add_u32 s10, s10, 0x2000
	s_addc_u32 s11, s11, 0
	global_load_dword v109, v124, s[10:11] nt
	s_add_u32 s10, s10, 0x2000
	s_addc_u32 s11, s11, 0
	global_load_dword v110, v124, s[10:11] nt
	s_add_u32 s10, s10, 0x2000
	s_addc_u32 s11, s11, 0
	global_load_dword v111, v124, s[10:11] nt
	s_add_u32 s10, s10, 0x2000
	s_addc_u32 s11, s11, 0
	global_load_dword v112, v124, s[10:11] nt
	s_add_u32 s10, s10, 0x2000
	s_addc_u32 s11, s11, 0
	global_load_dword v113, v124, s[10:11] nt
	s_add_u32 s10, s10, 0x2000
	s_addc_u32 s11, s11, 0
	global_load_dword v114, v124, s[10:11] nt
	s_add_u32 s10, s10, 0x2000
	s_addc_u32 s11, s11, 0
	global_load_dword v115, v124, s[10:11] nt
	s_add_u32 s10, s10, 0x2000
	s_addc_u32 s11, s11, 0
	global_load_dword v116, v124, s[10:11] nt
	s_add_u32 s10, s10, 0x2000
	s_addc_u32 s11, s11, 0
	global_load_dword v117, v124, s[10:11] nt
	s_add_u32 s10, s10, 0x2000
	s_addc_u32 s11, s11, 0
	global_load_dword v118, v124, s[10:11] nt
	s_add_u32 s10, s10, 0x2000
	s_addc_u32 s11, s11, 0
	global_load_dword v119, v124, s[10:11] nt
	s_add_u32 s10, s10, 0x2000
	s_addc_u32 s11, s11, 0
	global_load_dword v120, v124, s[10:11] nt
	s_add_u32 s10, s10, 0x2000
	s_addc_u32 s11, s11, 0
	global_load_dword v121, v124, s[10:11] nt
	s_add_u32 s10, s10, 0x2000
	s_addc_u32 s11, s11, 0
	global_load_dword v122, v124, s[10:11] nt
	s_add_u32 s10, s10, 0x2000
	s_addc_u32 s11, s11, 0
	global_load_dword v123, v124, s[10:11] nt
	s_waitcnt vmcnt(62)
	ds_write2_b32 v4, v60, v61 offset1:65
	s_waitcnt vmcnt(60)
	ds_write2_b32 v4, v62, v63 offset0:130 offset1:195
	v_add_u32_e32 v125, 0x400, v4
	s_waitcnt vmcnt(58)
	ds_write2_b32 v125, v64, v65 offset0:4 offset1:69
	s_waitcnt vmcnt(56)
	ds_write2_b32 v125, v66, v67 offset0:134 offset1:199
	v_add_u32_e32 v125, 0x800, v4
	s_waitcnt vmcnt(54)
	ds_write2_b32 v125, v68, v69 offset0:8 offset1:73
	s_waitcnt vmcnt(52)
	ds_write2_b32 v125, v70, v71 offset0:138 offset1:203
	v_add_u32_e32 v125, 0xc00, v4
	s_waitcnt vmcnt(50)
	ds_write2_b32 v125, v72, v73 offset0:12 offset1:77
	s_waitcnt vmcnt(48)
	ds_write2_b32 v125, v74, v75 offset0:142 offset1:207
	v_add_u32_e32 v125, 0x1040, v4
	s_waitcnt vmcnt(46)
	ds_write2_b32 v125, v76, v77 offset1:65
	s_waitcnt vmcnt(44)
	ds_write2_b32 v125, v78, v79 offset0:130 offset1:195
	v_add_u32_e32 v125, 0x1440, v4
	s_waitcnt vmcnt(42)
	ds_write2_b32 v125, v80, v81 offset0:4 offset1:69
	s_waitcnt vmcnt(40)
	ds_write2_b32 v125, v82, v83 offset0:134 offset1:199
	v_add_u32_e32 v125, 0x1840, v4
	s_waitcnt vmcnt(38)
	ds_write2_b32 v125, v84, v85 offset0:8 offset1:73
	s_waitcnt vmcnt(36)
	ds_write2_b32 v125, v86, v87 offset0:138 offset1:203
	v_add_u32_e32 v125, 0x1c40, v4
	s_waitcnt vmcnt(34)
	ds_write2_b32 v125, v88, v89 offset0:12 offset1:77
	s_waitcnt vmcnt(32)
	ds_write2_b32 v125, v90, v91 offset0:142 offset1:207
	v_add_u32_e32 v125, 0x2080, v4
	s_waitcnt vmcnt(30)
	ds_write2_b32 v125, v92, v93 offset1:65
	s_waitcnt vmcnt(28)
	ds_write2_b32 v125, v94, v95 offset0:130 offset1:195
	v_add_u32_e32 v125, 0x2480, v4
	s_waitcnt vmcnt(26)
	ds_write2_b32 v125, v96, v97 offset0:4 offset1:69
	s_waitcnt vmcnt(24)
	ds_write2_b32 v125, v98, v99 offset0:134 offset1:199
	v_add_u32_e32 v125, 0x2880, v4
	s_waitcnt vmcnt(22)
	ds_write2_b32 v125, v100, v101 offset0:8 offset1:73
	s_waitcnt vmcnt(20)
	ds_write2_b32 v125, v102, v103 offset0:138 offset1:203
	v_add_u32_e32 v125, 0x2c80, v4
	s_waitcnt vmcnt(18)
	ds_write2_b32 v125, v104, v105 offset0:12 offset1:77
	s_waitcnt vmcnt(16)
	ds_write2_b32 v125, v106, v107 offset0:142 offset1:207
	v_add_u32_e32 v125, 0x30c0, v4
	s_waitcnt vmcnt(14)
	ds_write2_b32 v125, v108, v109 offset1:65
	s_waitcnt vmcnt(12)
	ds_write2_b32 v125, v110, v111 offset0:130 offset1:195
	v_add_u32_e32 v125, 0x34c0, v4
	s_waitcnt vmcnt(10)
	ds_write2_b32 v125, v112, v113 offset0:4 offset1:69
	s_waitcnt vmcnt(8)
	ds_write2_b32 v125, v114, v115 offset0:134 offset1:199
	v_add_u32_e32 v125, 0x38c0, v4
	s_waitcnt vmcnt(6)
	ds_write2_b32 v125, v116, v117 offset0:8 offset1:73
	s_waitcnt vmcnt(4)
	ds_write2_b32 v125, v118, v119 offset0:138 offset1:203
	v_add_u32_e32 v125, 0x3cc0, v4
	s_waitcnt vmcnt(2)
	ds_write2_b32 v125, v120, v121 offset0:12 offset1:77
	s_waitcnt vmcnt(0)
	ds_write2_b32 v125, v122, v123 offset0:142 offset1:207
	v_add_u32_e32 v4, 0xffffe800, v1
	v_lshrrev_b32_e32 v25, 5, v4
	v_lshlrev_b32_e32 v27, 6, v4
	v_lshlrev_b32_e32 v29, 11, v25
	v_lshlrev_b32_e32 v4, 7, v25
	v_sub_u32_e32 v25, v27, v29
	s_waitcnt lgkmcnt(0)
	v_or_b32_e32 v60, v25, v39
	ds_read2_b32 v[34:35], v40 offset1:65
	v_ashrrev_i32_e32 v61, 31, v60
	s_waitcnt lgkmcnt(0)
	v_cvt_pk_bf16_f32 v34, v34, v35
	ds_read2_b32 v[36:37], v40 offset0:130 offset1:195
	v_add_u32_e32 v23, 0x400, v40
	v_lshl_add_u64 v[58:59], v[20:21], 0, v[4:5]
	v_lshlrev_b64 v[60:61], 13, v[60:61]
	s_waitcnt lgkmcnt(0)
	v_cvt_pk_bf16_f32 v35, v36, v37
	ds_read2_b32 v[36:37], v23 offset0:4 offset1:69
	v_lshl_add_u64 v[60:61], v[58:59], 0, v[60:61]
	s_waitcnt lgkmcnt(0)
	v_cvt_pk_bf16_f32 v36, v36, v37
	ds_read2_b32 v[56:57], v23 offset0:134 offset1:199
	s_waitcnt lgkmcnt(0)
	v_cvt_pk_bf16_f32 v37, v56, v57
	global_store_dwordx4 v[60:61], v[34:37], off
	v_or_b32_e32 v60, v25, v41
	v_ashrrev_i32_e32 v61, 31, v60
	ds_read2_b32 v[56:57], v40 offset0:8 offset1:73
	s_waitcnt lgkmcnt(0)
	v_cvt_pk_bf16_f32 v34, v56, v57
	ds_read2_b32 v[36:37], v40 offset0:138 offset1:203
	v_lshlrev_b64 v[60:61], 13, v[60:61]
	s_waitcnt lgkmcnt(0)
	v_cvt_pk_bf16_f32 v35, v36, v37
	ds_read2_b32 v[36:37], v23 offset0:12 offset1:77
	v_lshl_add_u64 v[60:61], v[58:59], 0, v[60:61]
	s_waitcnt lgkmcnt(0)
	v_cvt_pk_bf16_f32 v36, v36, v37
	ds_read2_b32 v[56:57], v23 offset0:142 offset1:207
	s_waitcnt lgkmcnt(0)
	v_cvt_pk_bf16_f32 v37, v56, v57
	global_store_dwordx4 v[60:61], v[34:37], off
	v_or_b32_e32 v60, v25, v42
	v_ashrrev_i32_e32 v61, 31, v60
	ds_read2_b32 v[56:57], v40 offset0:16 offset1:81
	s_waitcnt lgkmcnt(0)
	v_cvt_pk_bf16_f32 v34, v56, v57
	ds_read2_b32 v[36:37], v40 offset0:146 offset1:211
	v_lshlrev_b64 v[60:61], 13, v[60:61]
	s_waitcnt lgkmcnt(0)
	v_cvt_pk_bf16_f32 v35, v36, v37
	ds_read2_b32 v[36:37], v23 offset0:20 offset1:85
	v_lshl_add_u64 v[60:61], v[58:59], 0, v[60:61]
	s_waitcnt lgkmcnt(0)
	v_cvt_pk_bf16_f32 v36, v36, v37
	ds_read2_b32 v[56:57], v23 offset0:150 offset1:215
	s_waitcnt lgkmcnt(0)
	v_cvt_pk_bf16_f32 v37, v56, v57
	global_store_dwordx4 v[60:61], v[34:37], off
	v_or_b32_e32 v60, v25, v43
	v_ashrrev_i32_e32 v61, 31, v60
	ds_read2_b32 v[56:57], v40 offset0:24 offset1:89
	s_waitcnt lgkmcnt(0)
	v_cvt_pk_bf16_f32 v34, v56, v57
	ds_read2_b32 v[36:37], v40 offset0:154 offset1:219
	v_lshlrev_b64 v[60:61], 13, v[60:61]
	s_waitcnt lgkmcnt(0)
	v_cvt_pk_bf16_f32 v35, v36, v37
	ds_read2_b32 v[36:37], v23 offset0:28 offset1:93
	v_lshl_add_u64 v[60:61], v[58:59], 0, v[60:61]
	s_waitcnt lgkmcnt(0)
	v_cvt_pk_bf16_f32 v36, v36, v37
	ds_read2_b32 v[56:57], v23 offset0:158 offset1:223
	s_waitcnt lgkmcnt(0)
	v_cvt_pk_bf16_f32 v37, v56, v57
	global_store_dwordx4 v[60:61], v[34:37], off
	v_or_b32_e32 v60, v25, v44
	v_ashrrev_i32_e32 v61, 31, v60
	ds_read2_b32 v[56:57], v40 offset0:32 offset1:97
	s_waitcnt lgkmcnt(0)
	v_cvt_pk_bf16_f32 v34, v56, v57
	ds_read2_b32 v[36:37], v40 offset0:162 offset1:227
	v_lshlrev_b64 v[60:61], 13, v[60:61]
	s_waitcnt lgkmcnt(0)
	v_cvt_pk_bf16_f32 v35, v36, v37
	ds_read2_b32 v[36:37], v23 offset0:36 offset1:101
	v_lshl_add_u64 v[60:61], v[58:59], 0, v[60:61]
	s_waitcnt lgkmcnt(0)
	v_cvt_pk_bf16_f32 v36, v36, v37
	ds_read2_b32 v[56:57], v23 offset0:166 offset1:231
	s_waitcnt lgkmcnt(0)
	v_cvt_pk_bf16_f32 v37, v56, v57
	global_store_dwordx4 v[60:61], v[34:37], off
	v_or_b32_e32 v60, v25, v45
	v_ashrrev_i32_e32 v61, 31, v60
	ds_read2_b32 v[56:57], v40 offset0:40 offset1:105
	s_waitcnt lgkmcnt(0)
	v_cvt_pk_bf16_f32 v34, v56, v57
	ds_read2_b32 v[36:37], v40 offset0:170 offset1:235
	v_lshlrev_b64 v[60:61], 13, v[60:61]
	s_waitcnt lgkmcnt(0)
	v_cvt_pk_bf16_f32 v35, v36, v37
	ds_read2_b32 v[36:37], v23 offset0:44 offset1:109
	v_lshl_add_u64 v[60:61], v[58:59], 0, v[60:61]
	s_waitcnt lgkmcnt(0)
	v_cvt_pk_bf16_f32 v36, v36, v37
	ds_read2_b32 v[56:57], v23 offset0:174 offset1:239
	s_waitcnt lgkmcnt(0)
	v_cvt_pk_bf16_f32 v37, v56, v57
	global_store_dwordx4 v[60:61], v[34:37], off
	v_or_b32_e32 v60, v25, v46
	ds_read2_b32 v[56:57], v40 offset0:48 offset1:113
	s_waitcnt lgkmcnt(0)
	v_cvt_pk_bf16_f32 v34, v56, v57
	ds_read2_b32 v[36:37], v40 offset0:178 offset1:243
	v_ashrrev_i32_e32 v61, 31, v60
	s_waitcnt lgkmcnt(0)
	v_cvt_pk_bf16_f32 v35, v36, v37
	ds_read2_b32 v[36:37], v23 offset0:52 offset1:117
	v_lshlrev_b64 v[60:61], 13, v[60:61]
	s_waitcnt lgkmcnt(0)
	v_cvt_pk_bf16_f32 v36, v36, v37
	ds_read2_b32 v[56:57], v23 offset0:182 offset1:247
	s_waitcnt lgkmcnt(0)
	v_cvt_pk_bf16_f32 v37, v56, v57
	v_lshl_add_u64 v[60:61], v[58:59], 0, v[60:61]
	ds_read2_b32 v[56:57], v40 offset0:56 offset1:121
	global_store_dwordx4 v[60:61], v[34:37], off
	v_or_b32_e32 v60, v25, v47
	v_ashrrev_i32_e32 v61, 31, v60
	s_waitcnt lgkmcnt(0)
	v_cvt_pk_bf16_f32 v34, v56, v57
	ds_read2_b32 v[36:37], v40 offset0:186 offset1:251
	s_waitcnt lgkmcnt(0)
	v_cvt_pk_bf16_f32 v35, v36, v37
	ds_read2_b32 v[36:37], v23 offset0:60 offset1:125
	s_waitcnt lgkmcnt(0)
	v_cvt_pk_bf16_f32 v36, v36, v37
	ds_read2_b32 v[56:57], v23 offset0:190 offset1:255
	v_lshlrev_b64 v[60:61], 13, v[60:61]
	s_waitcnt lgkmcnt(0)
	v_cvt_pk_bf16_f32 v37, v56, v57
	v_lshl_add_u64 v[56:57], v[58:59], 0, v[60:61]
	global_store_dwordx4 v[56:57], v[34:37], off
	s_waitcnt lgkmcnt(0)

.LBB0_68:
	v_readfirstlane_b32 s8, v36
	v_readfirstlane_b32 s9, v37
	s_nop 4
	v_subrev_u32_e32 v124, s8, v36
	global_load_dword v60, v124, s[8:9] nt
	s_add_u32 s8, s8, 0xc000
	s_addc_u32 s9, s9, 0
	global_load_dword v61, v124, s[8:9] nt
	s_add_u32 s8, s8, 0xc000
	s_addc_u32 s9, s9, 0
	global_load_dword v62, v124, s[8:9] nt
	s_add_u32 s8, s8, 0xc000
	s_addc_u32 s9, s9, 0
	global_load_dword v63, v124, s[8:9] nt
	s_add_u32 s8, s8, 0xc000
	s_addc_u32 s9, s9, 0
	global_load_dword v64, v124, s[8:9] nt
	s_add_u32 s8, s8, 0xc000
	s_addc_u32 s9, s9, 0
	global_load_dword v65, v124, s[8:9] nt
	s_add_u32 s8, s8, 0xc000
	s_addc_u32 s9, s9, 0
	global_load_dword v66, v124, s[8:9] nt
	s_add_u32 s8, s8, 0xc000
	s_addc_u32 s9, s9, 0
	global_load_dword v67, v124, s[8:9] nt
	s_add_u32 s8, s8, 0xc000
	s_addc_u32 s9, s9, 0
	global_load_dword v68, v124, s[8:9] nt
	s_add_u32 s8, s8, 0xc000
	s_addc_u32 s9, s9, 0
	global_load_dword v69, v124, s[8:9] nt
	s_add_u32 s8, s8, 0xc000
	s_addc_u32 s9, s9, 0
	global_load_dword v70, v124, s[8:9] nt
	s_add_u32 s8, s8, 0xc000
	s_addc_u32 s9, s9, 0
	global_load_dword v71, v124, s[8:9] nt
	s_add_u32 s8, s8, 0xc000
	s_addc_u32 s9, s9, 0
	global_load_dword v72, v124, s[8:9] nt
	s_add_u32 s8, s8, 0xc000
	s_addc_u32 s9, s9, 0
	global_load_dword v73, v124, s[8:9] nt
	s_add_u32 s8, s8, 0xc000
	s_addc_u32 s9, s9, 0
	global_load_dword v74, v124, s[8:9] nt
	s_add_u32 s8, s8, 0xc000
	s_addc_u32 s9, s9, 0
	global_load_dword v75, v124, s[8:9] nt
	s_add_u32 s8, s8, 0xc000
	s_addc_u32 s9, s9, 0
	global_load_dword v76, v124, s[8:9] nt
	s_add_u32 s8, s8, 0xc000
	s_addc_u32 s9, s9, 0
	global_load_dword v77, v124, s[8:9] nt
	s_add_u32 s8, s8, 0xc000
	s_addc_u32 s9, s9, 0
	global_load_dword v78, v124, s[8:9] nt
	s_add_u32 s8, s8, 0xc000
	s_addc_u32 s9, s9, 0
	global_load_dword v79, v124, s[8:9] nt
	s_add_u32 s8, s8, 0xc000
	s_addc_u32 s9, s9, 0
	global_load_dword v80, v124, s[8:9] nt
	s_add_u32 s8, s8, 0xc000
	s_addc_u32 s9, s9, 0
	global_load_dword v81, v124, s[8:9] nt
	s_add_u32 s8, s8, 0xc000
	s_addc_u32 s9, s9, 0
	global_load_dword v82, v124, s[8:9] nt
	s_add_u32 s8, s8, 0xc000
	s_addc_u32 s9, s9, 0
	global_load_dword v83, v124, s[8:9] nt
	s_add_u32 s8, s8, 0xc000
	s_addc_u32 s9, s9, 0
	global_load_dword v84, v124, s[8:9] nt
	s_add_u32 s8, s8, 0xc000
	s_addc_u32 s9, s9, 0
	global_load_dword v85, v124, s[8:9] nt
	s_add_u32 s8, s8, 0xc000
	s_addc_u32 s9, s9, 0
	global_load_dword v86, v124, s[8:9] nt
	s_add_u32 s8, s8, 0xc000
	s_addc_u32 s9, s9, 0
	global_load_dword v87, v124, s[8:9] nt
	s_add_u32 s8, s8, 0xc000
	s_addc_u32 s9, s9, 0
	global_load_dword v88, v124, s[8:9] nt
	s_add_u32 s8, s8, 0xc000
	s_addc_u32 s9, s9, 0
	global_load_dword v89, v124, s[8:9] nt
	s_add_u32 s8, s8, 0xc000
	s_addc_u32 s9, s9, 0
	global_load_dword v90, v124, s[8:9] nt
	s_add_u32 s8, s8, 0xc000
	s_addc_u32 s9, s9, 0
	global_load_dword v91, v124, s[8:9] nt
	s_add_u32 s8, s8, 0xc000
	s_addc_u32 s9, s9, 0
	global_load_dword v92, v124, s[8:9] nt
	s_add_u32 s8, s8, 0xc000
	s_addc_u32 s9, s9, 0
	global_load_dword v93, v124, s[8:9] nt
	s_add_u32 s8, s8, 0xc000
	s_addc_u32 s9, s9, 0
	global_load_dword v94, v124, s[8:9] nt
	s_add_u32 s8, s8, 0xc000
	s_addc_u32 s9, s9, 0
	global_load_dword v95, v124, s[8:9] nt
	s_add_u32 s8, s8, 0xc000
	s_addc_u32 s9, s9, 0
	global_load_dword v96, v124, s[8:9] nt
	s_add_u32 s8, s8, 0xc000
	s_addc_u32 s9, s9, 0
	global_load_dword v97, v124, s[8:9] nt
	s_add_u32 s8, s8, 0xc000
	s_addc_u32 s9, s9, 0
	global_load_dword v98, v124, s[8:9] nt
	s_add_u32 s8, s8, 0xc000
	s_addc_u32 s9, s9, 0
	global_load_dword v99, v124, s[8:9] nt
	s_add_u32 s8, s8, 0xc000
	s_addc_u32 s9, s9, 0
	global_load_dword v100, v124, s[8:9] nt
	s_add_u32 s8, s8, 0xc000
	s_addc_u32 s9, s9, 0
	global_load_dword v101, v124, s[8:9] nt
	s_add_u32 s8, s8, 0xc000
	s_addc_u32 s9, s9, 0
	global_load_dword v102, v124, s[8:9] nt
	s_add_u32 s8, s8, 0xc000
	s_addc_u32 s9, s9, 0
	global_load_dword v103, v124, s[8:9] nt
	s_add_u32 s8, s8, 0xc000
	s_addc_u32 s9, s9, 0
	global_load_dword v104, v124, s[8:9] nt
	s_add_u32 s8, s8, 0xc000
	s_addc_u32 s9, s9, 0
	global_load_dword v105, v124, s[8:9] nt
	s_add_u32 s8, s8, 0xc000
	s_addc_u32 s9, s9, 0
	global_load_dword v106, v124, s[8:9] nt
	s_add_u32 s8, s8, 0xc000
	s_addc_u32 s9, s9, 0
	global_load_dword v107, v124, s[8:9] nt
	s_add_u32 s8, s8, 0xc000
	s_addc_u32 s9, s9, 0
	global_load_dword v108, v124, s[8:9] nt
	s_add_u32 s8, s8, 0xc000
	s_addc_u32 s9, s9, 0
	global_load_dword v109, v124, s[8:9] nt
	s_add_u32 s8, s8, 0xc000
	s_addc_u32 s9, s9, 0
	global_load_dword v110, v124, s[8:9] nt
	s_add_u32 s8, s8, 0xc000
	s_addc_u32 s9, s9, 0
	global_load_dword v111, v124, s[8:9] nt
	s_add_u32 s8, s8, 0xc000
	s_addc_u32 s9, s9, 0
	global_load_dword v112, v124, s[8:9] nt
	s_add_u32 s8, s8, 0xc000
	s_addc_u32 s9, s9, 0
	global_load_dword v113, v124, s[8:9] nt
	s_add_u32 s8, s8, 0xc000
	s_addc_u32 s9, s9, 0
	global_load_dword v114, v124, s[8:9] nt
	s_add_u32 s8, s8, 0xc000
	s_addc_u32 s9, s9, 0
	global_load_dword v115, v124, s[8:9] nt
	s_add_u32 s8, s8, 0xc000
	s_addc_u32 s9, s9, 0
	global_load_dword v116, v124, s[8:9] nt
	s_add_u32 s8, s8, 0xc000
	s_addc_u32 s9, s9, 0
	global_load_dword v117, v124, s[8:9] nt
	s_add_u32 s8, s8, 0xc000
	s_addc_u32 s9, s9, 0
	global_load_dword v118, v124, s[8:9] nt
	s_add_u32 s8, s8, 0xc000
	s_addc_u32 s9, s9, 0
	global_load_dword v119, v124, s[8:9] nt
	s_add_u32 s8, s8, 0xc000
	s_addc_u32 s9, s9, 0
	global_load_dword v120, v124, s[8:9] nt
	s_add_u32 s8, s8, 0xc000
	s_addc_u32 s9, s9, 0
	global_load_dword v121, v124, s[8:9] nt
	s_add_u32 s8, s8, 0xc000
	s_addc_u32 s9, s9, 0
	global_load_dword v122, v124, s[8:9] nt
	s_add_u32 s8, s8, 0xc000
	s_addc_u32 s9, s9, 0
	global_load_dword v123, v124, s[8:9] nt
	s_waitcnt vmcnt(62)
	ds_write2_b32 v23, v60, v61 offset1:65
	s_waitcnt vmcnt(60)
	ds_write2_b32 v23, v62, v63 offset0:130 offset1:195
	v_add_u32_e32 v125, 0x400, v23
	s_waitcnt vmcnt(58)
	ds_write2_b32 v125, v64, v65 offset0:4 offset1:69
	s_waitcnt vmcnt(56)
	ds_write2_b32 v125, v66, v67 offset0:134 offset1:199
	v_add_u32_e32 v125, 0x800, v23
	s_waitcnt vmcnt(54)
	ds_write2_b32 v125, v68, v69 offset0:8 offset1:73
	s_waitcnt vmcnt(52)
	ds_write2_b32 v125, v70, v71 offset0:138 offset1:203
	v_add_u32_e32 v125, 0xc00, v23
	s_waitcnt vmcnt(50)
	ds_write2_b32 v125, v72, v73 offset0:12 offset1:77
	s_waitcnt vmcnt(48)
	ds_write2_b32 v125, v74, v75 offset0:142 offset1:207
	v_add_u32_e32 v125, 0x1040, v23
	s_waitcnt vmcnt(46)
	ds_write2_b32 v125, v76, v77 offset1:65
	s_waitcnt vmcnt(44)
	ds_write2_b32 v125, v78, v79 offset0:130 offset1:195
	v_add_u32_e32 v125, 0x1440, v23
	s_waitcnt vmcnt(42)
	ds_write2_b32 v125, v80, v81 offset0:4 offset1:69
	s_waitcnt vmcnt(40)
	ds_write2_b32 v125, v82, v83 offset0:134 offset1:199
	v_add_u32_e32 v125, 0x1840, v23
	s_waitcnt vmcnt(38)
	ds_write2_b32 v125, v84, v85 offset0:8 offset1:73
	s_waitcnt vmcnt(36)
	ds_write2_b32 v125, v86, v87 offset0:138 offset1:203
	v_add_u32_e32 v125, 0x1c40, v23
	s_waitcnt vmcnt(34)
	ds_write2_b32 v125, v88, v89 offset0:12 offset1:77
	s_waitcnt vmcnt(32)
	ds_write2_b32 v125, v90, v91 offset0:142 offset1:207
	v_add_u32_e32 v125, 0x2080, v23
	s_waitcnt vmcnt(30)
	ds_write2_b32 v125, v92, v93 offset1:65
	s_waitcnt vmcnt(28)
	ds_write2_b32 v125, v94, v95 offset0:130 offset1:195
	v_add_u32_e32 v125, 0x2480, v23
	s_waitcnt vmcnt(26)
	ds_write2_b32 v125, v96, v97 offset0:4 offset1:69
	s_waitcnt vmcnt(24)
	ds_write2_b32 v125, v98, v99 offset0:134 offset1:199
	v_add_u32_e32 v125, 0x2880, v23
	s_waitcnt vmcnt(22)
	ds_write2_b32 v125, v100, v101 offset0:8 offset1:73
	s_waitcnt vmcnt(20)
	ds_write2_b32 v125, v102, v103 offset0:138 offset1:203
	v_add_u32_e32 v125, 0x2c80, v23
	s_waitcnt vmcnt(18)
	ds_write2_b32 v125, v104, v105 offset0:12 offset1:77
	s_waitcnt vmcnt(16)
	ds_write2_b32 v125, v106, v107 offset0:142 offset1:207
	v_add_u32_e32 v125, 0x30c0, v23
	s_waitcnt vmcnt(14)
	ds_write2_b32 v125, v108, v109 offset1:65
	s_waitcnt vmcnt(12)
	ds_write2_b32 v125, v110, v111 offset0:130 offset1:195
	v_add_u32_e32 v125, 0x34c0, v23
	s_waitcnt vmcnt(10)
	ds_write2_b32 v125, v112, v113 offset0:4 offset1:69
	s_waitcnt vmcnt(8)
	ds_write2_b32 v125, v114, v115 offset0:134 offset1:199
	v_add_u32_e32 v125, 0x38c0, v23
	s_waitcnt vmcnt(6)
	ds_write2_b32 v125, v116, v117 offset0:8 offset1:73
	s_waitcnt vmcnt(4)
	ds_write2_b32 v125, v118, v119 offset0:138 offset1:203
	v_add_u32_e32 v125, 0x3cc0, v23
	s_waitcnt vmcnt(2)
	ds_write2_b32 v125, v120, v121 offset0:12 offset1:77
	s_waitcnt vmcnt(0)
	ds_write2_b32 v125, v122, v123 offset0:142 offset1:207
	v_mul_lo_u32 v4, v4, s36
	v_add_lshl_u32 v4, v4, v1, 6
	s_waitcnt lgkmcnt(0)
	v_lshl_add_u64 v[60:61], v[34:35], 1, v[6:7]
	v_or_b32_e32 v34, v4, v39
	ds_read2_b32 v[36:37], v40 offset1:65
	v_ashrrev_i32_e32 v35, 31, v34
	s_waitcnt lgkmcnt(0)
	v_cvt_pk_bf16_f32 v56, v36, v37
	ds_read2_b32 v[36:37], v40 offset0:130 offset1:195
	v_add_u32_e32 v23, 0x400, v40
	v_lshlrev_b64 v[34:35], 12, v[34:35]
	s_waitcnt lgkmcnt(0)
	v_cvt_pk_bf16_f32 v57, v36, v37
	ds_read2_b32 v[36:37], v23 offset0:4 offset1:69
	s_waitcnt lgkmcnt(0)
	v_cvt_pk_bf16_f32 v58, v36, v37
	v_lshl_add_u64 v[34:35], v[60:61], 0, v[34:35]
	ds_read2_b32 v[36:37], v23 offset0:134 offset1:199
	s_waitcnt lgkmcnt(0)
	v_cvt_pk_bf16_f32 v59, v36, v37
	global_store_dwordx4 v[34:35], v[56:59], off
	ds_read2_b32 v[36:37], v40 offset0:8 offset1:73
	s_waitcnt lgkmcnt(0)
	v_cvt_pk_bf16_f32 v34, v36, v37
	ds_read2_b32 v[36:37], v40 offset0:138 offset1:203
	v_or_b32_e32 v58, v4, v41
	v_ashrrev_i32_e32 v59, 31, v58
	v_lshlrev_b64 v[58:59], 12, v[58:59]
	s_waitcnt lgkmcnt(0)
	v_cvt_pk_bf16_f32 v35, v36, v37
	ds_read2_b32 v[36:37], v23 offset0:12 offset1:77
	v_lshl_add_u64 v[58:59], v[60:61], 0, v[58:59]
	s_waitcnt lgkmcnt(0)
	v_cvt_pk_bf16_f32 v36, v36, v37
	ds_read2_b32 v[56:57], v23 offset0:142 offset1:207
	s_waitcnt lgkmcnt(0)
	v_cvt_pk_bf16_f32 v37, v56, v57
	global_store_dwordx4 v[58:59], v[34:37], off
	v_or_b32_e32 v58, v4, v42
	v_ashrrev_i32_e32 v59, 31, v58
	ds_read2_b32 v[56:57], v40 offset0:16 offset1:81
	s_waitcnt lgkmcnt(0)
	v_cvt_pk_bf16_f32 v34, v56, v57
	ds_read2_b32 v[36:37], v40 offset0:146 offset1:211
	v_lshlrev_b64 v[58:59], 12, v[58:59]
	s_waitcnt lgkmcnt(0)
	v_cvt_pk_bf16_f32 v35, v36, v37
	ds_read2_b32 v[36:37], v23 offset0:20 offset1:85
	v_lshl_add_u64 v[58:59], v[60:61], 0, v[58:59]
	s_waitcnt lgkmcnt(0)
	v_cvt_pk_bf16_f32 v36, v36, v37
	ds_read2_b32 v[56:57], v23 offset0:150 offset1:215
	s_waitcnt lgkmcnt(0)
	v_cvt_pk_bf16_f32 v37, v56, v57
	global_store_dwordx4 v[58:59], v[34:37], off
	v_or_b32_e32 v58, v4, v43
	v_ashrrev_i32_e32 v59, 31, v58
	ds_read2_b32 v[56:57], v40 offset0:24 offset1:89
	s_waitcnt lgkmcnt(0)
	v_cvt_pk_bf16_f32 v34, v56, v57
	ds_read2_b32 v[36:37], v40 offset0:154 offset1:219
	v_lshlrev_b64 v[58:59], 12, v[58:59]
	s_waitcnt lgkmcnt(0)
	v_cvt_pk_bf16_f32 v35, v36, v37
	ds_read2_b32 v[36:37], v23 offset0:28 offset1:93
	v_lshl_add_u64 v[58:59], v[60:61], 0, v[58:59]
	s_waitcnt lgkmcnt(0)
	v_cvt_pk_bf16_f32 v36, v36, v37
	ds_read2_b32 v[56:57], v23 offset0:158 offset1:223
	s_waitcnt lgkmcnt(0)
	v_cvt_pk_bf16_f32 v37, v56, v57
	global_store_dwordx4 v[58:59], v[34:37], off
	v_or_b32_e32 v58, v4, v44
	v_ashrrev_i32_e32 v59, 31, v58
	ds_read2_b32 v[56:57], v40 offset0:32 offset1:97
	s_waitcnt lgkmcnt(0)
	v_cvt_pk_bf16_f32 v34, v56, v57
	ds_read2_b32 v[36:37], v40 offset0:162 offset1:227
	v_lshlrev_b64 v[58:59], 12, v[58:59]
	s_waitcnt lgkmcnt(0)
	v_cvt_pk_bf16_f32 v35, v36, v37
	ds_read2_b32 v[36:37], v23 offset0:36 offset1:101
	v_lshl_add_u64 v[58:59], v[60:61], 0, v[58:59]
	s_waitcnt lgkmcnt(0)
	v_cvt_pk_bf16_f32 v36, v36, v37
	ds_read2_b32 v[56:57], v23 offset0:166 offset1:231
	s_waitcnt lgkmcnt(0)
	v_cvt_pk_bf16_f32 v37, v56, v57
	global_store_dwordx4 v[58:59], v[34:37], off
	v_or_b32_e32 v58, v4, v45
	v_ashrrev_i32_e32 v59, 31, v58
	ds_read2_b32 v[56:57], v40 offset0:40 offset1:105
	s_waitcnt lgkmcnt(0)
	v_cvt_pk_bf16_f32 v34, v56, v57
	ds_read2_b32 v[36:37], v40 offset0:170 offset1:235
	v_lshlrev_b64 v[58:59], 12, v[58:59]
	s_waitcnt lgkmcnt(0)
	v_cvt_pk_bf16_f32 v35, v36, v37
	ds_read2_b32 v[36:37], v23 offset0:44 offset1:109
	v_lshl_add_u64 v[58:59], v[60:61], 0, v[58:59]
	s_waitcnt lgkmcnt(0)
	v_cvt_pk_bf16_f32 v36, v36, v37
	ds_read2_b32 v[56:57], v23 offset0:174 offset1:239
	s_waitcnt lgkmcnt(0)
	v_cvt_pk_bf16_f32 v37, v56, v57
	global_store_dwordx4 v[58:59], v[34:37], off
	v_or_b32_e32 v58, v4, v46
	ds_read2_b32 v[56:57], v40 offset0:48 offset1:113
	s_waitcnt lgkmcnt(0)
	v_cvt_pk_bf16_f32 v34, v56, v57
	ds_read2_b32 v[36:37], v40 offset0:178 offset1:243
	v_ashrrev_i32_e32 v59, 31, v58
	s_waitcnt lgkmcnt(0)
	v_cvt_pk_bf16_f32 v35, v36, v37
	ds_read2_b32 v[36:37], v23 offset0:52 offset1:117
	v_lshlrev_b64 v[58:59], 12, v[58:59]
	s_waitcnt lgkmcnt(0)
	v_cvt_pk_bf16_f32 v36, v36, v37
	ds_read2_b32 v[56:57], v23 offset0:182 offset1:247
	s_waitcnt lgkmcnt(0)
	v_cvt_pk_bf16_f32 v37, v56, v57
	v_lshl_add_u64 v[58:59], v[60:61], 0, v[58:59]
	ds_read2_b32 v[56:57], v40 offset0:56 offset1:121
	global_store_dwordx4 v[58:59], v[34:37], off
	v_or_b32_e32 v58, v4, v47
	v_ashrrev_i32_e32 v59, 31, v58
	s_waitcnt lgkmcnt(0)
	v_cvt_pk_bf16_f32 v34, v56, v57
	ds_read2_b32 v[36:37], v40 offset0:186 offset1:251
	s_waitcnt lgkmcnt(0)
	v_cvt_pk_bf16_f32 v35, v36, v37
	ds_read2_b32 v[36:37], v23 offset0:60 offset1:125
	s_waitcnt lgkmcnt(0)
	v_cvt_pk_bf16_f32 v36, v36, v37
	ds_read2_b32 v[56:57], v23 offset0:190 offset1:255
	v_lshlrev_b64 v[58:59], 12, v[58:59]
	s_waitcnt lgkmcnt(0)
	v_cvt_pk_bf16_f32 v37, v56, v57
	v_lshl_add_u64 v[56:57], v[60:61], 0, v[58:59]
	global_store_dwordx4 v[56:57], v[34:37], off
	s_waitcnt lgkmcnt(0)
	s_branch .LBB0_25
.LBB0_70:
	s_mul_i32 s82, s94, 8
	s_or_b64 exec, exec, s[0:1]
	v_lshrrev_b32_e32 v1, 20, v0
	v_lshrrev_b32_e32 v0, 10, v0
	v_or_b32_e32 v0, v0, v1
	s_movk_i32 s0, 0x3ff
	v_and_or_b32 v0, v0, s0, v172
	v_cmp_eq_u32_e32 vcc, 0, v0
	s_barrier
	s_barrier
	s_and_saveexec_b64 s[0:1], vcc
	s_cbranch_execz .LBB0_80
	buffer_wbl2 sc1
	s_waitcnt vmcnt(0)
	s_load_dwordx2 s[4:5], s[80:81], 0x58
	v_mov_b32_e32 v2, 0
	s_mov_b64 s[6:7], exec
	v_mbcnt_lo_u32_b32 v1, s6, 0
	v_mbcnt_hi_u32_b32 v1, s7, v1
	s_waitcnt lgkmcnt(0)
	global_load_dword v0, v2, s[4:5] offset:40
	v_cmp_eq_u32_e32 vcc, 0, v1
	s_and_saveexec_b64 s[8:9], vcc
	s_cbranch_execz .LBB0_73
	s_bcnt1_i32_b64 s2, s[6:7]
	v_mov_b32_e32 v3, s2
	global_atomic_add v3, v2, v3, s[4:5] offset:32 sc0
